# epilogue stores use 16 distinct data tuples (no reuse before completion); branch unit drains stores before refilling fragment registers
# speedup vs baseline: 1.0015x; 1.0012x over previous
.LBB0_372:
	s_add_u32 s8, s6, 0xfff80080
	s_addc_u32 s9, s7, -1
	s_add_i32 s21, 0, 0x10000
	v_add_u32_e32 v143, s21, v167
	ds_read_b128 v[148:151], v143
	ds_read_b128 v[152:155], v143 offset:1024
	ds_read_b128 v[156:159], v143 offset:2048
	ds_read_b128 v[160:163], v143 offset:3072
	s_cmp_eq_u32 s20, 28
	s_cselect_b32 s11, s17, s9
	s_cselect_b32 s10, s16, s8
	s_cselect_b32 s9, s19, s15
	s_cselect_b32 s8, s18, s13
	s_add_i32 s24, 0, 0x14000
	v_add_u32_e32 v143, s24, v167
	ds_read_b128 v[208:211], v143
	ds_read_b128 v[212:215], v143 offset:1024
	ds_read_b128 v[216:219], v143 offset:2048
	ds_read_b128 v[220:223], v143 offset:3072
	v_lshl_add_u64 v[164:165], s[6:7], 0, v[138:139]
	s_add_i32 m0, s40, 0xc000
	ds_read_b128 v[172:175], v171
	ds_read_b128 v[180:183], v171 offset:1024
	ds_read_b128 v[184:187], v171 offset:2048
	ds_read_b128 v[188:191], v171 offset:3072
	ds_read_b128 v[192:195], v171 offset:4096
	ds_read_b128 v[196:199], v171 offset:5120
	ds_read_b128 v[200:203], v171 offset:6144
	ds_read_b128 v[204:207], v171 offset:7168
	global_load_lds_dwordx4 v[164:165], off
	v_lshl_add_u64 v[164:165], s[6:7], 0, v[140:141]
	s_add_i32 m0, s40, 0xe000
	s_nop 0
	global_load_lds_dwordx4 v[164:165], off
	s_waitcnt lgkmcnt(0)
	s_barrier
	s_setprio 1
	v_mfma_f32_16x16x32_bf16 v[126:129], v[148:151], v[172:175], v[126:129]
	v_mfma_f32_16x16x32_bf16 v[122:125], v[156:159], v[172:175], v[122:125]
	v_mfma_f32_16x16x32_bf16 v[110:113], v[148:151], v[184:187], v[110:113]
	v_mfma_f32_16x16x32_bf16 v[106:109], v[156:159], v[184:187], v[106:109]
	v_mfma_f32_16x16x32_bf16 v[94:97], v[148:151], v[192:195], v[94:97]
	v_mfma_f32_16x16x32_bf16 v[90:93], v[156:159], v[192:195], v[90:93]
	v_mfma_f32_16x16x32_bf16 v[78:81], v[148:151], v[200:203], v[78:81]
	v_mfma_f32_16x16x32_bf16 v[74:77], v[156:159], v[200:203], v[74:77]
	v_mfma_f32_16x16x32_bf16 v[126:129], v[152:155], v[180:183], v[126:129]
	v_mfma_f32_16x16x32_bf16 v[122:125], v[160:163], v[180:183], v[122:125]
	v_mfma_f32_16x16x32_bf16 v[110:113], v[152:155], v[188:191], v[110:113]
	v_mfma_f32_16x16x32_bf16 v[106:109], v[160:163], v[188:191], v[106:109]
	v_mfma_f32_16x16x32_bf16 v[94:97], v[152:155], v[196:199], v[94:97]
	v_mfma_f32_16x16x32_bf16 v[90:93], v[160:163], v[196:199], v[90:93]
	v_mfma_f32_16x16x32_bf16 v[78:81], v[152:155], v[204:207], v[78:81]
	v_mfma_f32_16x16x32_bf16 v[74:77], v[160:163], v[204:207], v[74:77]
	v_mfma_f32_16x16x32_bf16 v[118:121], v[208:211], v[172:175], v[118:121]
	v_mfma_f32_16x16x32_bf16 v[114:117], v[216:219], v[172:175], v[114:117]
	v_mfma_f32_16x16x32_bf16 v[102:105], v[208:211], v[184:187], v[102:105]
	v_mfma_f32_16x16x32_bf16 v[98:101], v[216:219], v[184:187], v[98:101]
	v_mfma_f32_16x16x32_bf16 v[86:89], v[208:211], v[192:195], v[86:89]
	v_mfma_f32_16x16x32_bf16 v[82:85], v[216:219], v[192:195], v[82:85]
	v_mfma_f32_16x16x32_bf16 v[70:73], v[208:211], v[200:203], v[70:73]
	v_mfma_f32_16x16x32_bf16 v[66:69], v[216:219], v[200:203], v[66:69]
	v_mfma_f32_16x16x32_bf16 v[118:121], v[212:215], v[180:183], v[118:121]
	v_mfma_f32_16x16x32_bf16 v[114:117], v[220:223], v[180:183], v[114:117]
	v_mfma_f32_16x16x32_bf16 v[102:105], v[212:215], v[188:191], v[102:105]
	v_mfma_f32_16x16x32_bf16 v[98:101], v[220:223], v[188:191], v[98:101]
	v_mfma_f32_16x16x32_bf16 v[86:89], v[212:215], v[196:199], v[86:89]
	v_mfma_f32_16x16x32_bf16 v[82:85], v[220:223], v[196:199], v[82:85]
	v_mfma_f32_16x16x32_bf16 v[70:73], v[212:215], v[204:207], v[70:73]
	v_mfma_f32_16x16x32_bf16 v[66:69], v[220:223], v[204:207], v[66:69]
	s_setprio 0
	s_mov_b32 m0, s40
	v_lshl_add_u64 v[224:225], s[10:11], 0, v[136:137]
	s_barrier
	ds_read_b128 v[172:175], v171 offset:16384
	ds_read_b128 v[180:183], v171 offset:17408
	ds_read_b128 v[184:187], v171 offset:18432
	ds_read_b128 v[188:191], v171 offset:19456
	ds_read_b128 v[192:195], v171 offset:20480
	ds_read_b128 v[196:199], v171 offset:21504
	ds_read_b128 v[200:203], v171 offset:22528
	ds_read_b128 v[204:207], v171 offset:23552
	s_add_i32 s21, s21, s39
	v_lshl_add_u64 v[164:165], s[8:9], 0, v[134:135]
	s_mov_b32 m0, s21
	s_nop 0
	global_load_lds_dwordx4 v[164:165], off
	v_lshl_add_u64 v[176:177], s[8:9], 0, v[130:131]
	s_add_i32 m0, s21, 0x2000
	s_nop 0
	global_load_lds_dwordx4 v[176:177], off
	s_mov_b32 m0, s40
	s_nop 0
	global_load_lds_dwordx4 v[224:225], off
	v_lshl_add_u64 v[236:237], s[10:11], 0, v[132:133]
	s_mov_b32 m0, s41
	s_nop 0
	global_load_lds_dwordx4 v[236:237], off
	s_add_u32 s22, s8, 0x80000
	s_addc_u32 s23, s9, 0
	s_add_i32 s21, s24, s39
	s_mov_b32 m0, s21
	s_nop 0
	global_load_lds_dwordx4 v134, s[22:23]
	s_add_i32 m0, s21, 0x2000
	s_nop 0
	global_load_lds_dwordx4 v130, s[22:23]
	s_waitcnt vmcnt(6)
	s_waitcnt lgkmcnt(0)
	s_barrier
	s_setprio 1
	v_mfma_f32_16x16x32_bf16 v[62:65], v[148:151], v[172:175], v[62:65]
	v_mfma_f32_16x16x32_bf16 v[58:61], v[156:159], v[172:175], v[58:61]
	v_mfma_f32_16x16x32_bf16 v[46:49], v[148:151], v[184:187], v[46:49]
	v_mfma_f32_16x16x32_bf16 v[42:45], v[156:159], v[184:187], v[42:45]
	v_mfma_f32_16x16x32_bf16 v[28:31], v[148:151], v[192:195], v[28:31]
	v_mfma_f32_16x16x32_bf16 v[24:27], v[156:159], v[192:195], v[24:27]
	v_mfma_f32_16x16x32_bf16 v[12:15], v[148:151], v[200:203], v[12:15]
	v_mfma_f32_16x16x32_bf16 v[8:11], v[156:159], v[200:203], v[8:11]
	v_mfma_f32_16x16x32_bf16 v[62:65], v[152:155], v[180:183], v[62:65]
	v_mfma_f32_16x16x32_bf16 v[58:61], v[160:163], v[180:183], v[58:61]
	v_mfma_f32_16x16x32_bf16 v[46:49], v[152:155], v[188:191], v[46:49]
	v_mfma_f32_16x16x32_bf16 v[42:45], v[160:163], v[188:191], v[42:45]
	v_mfma_f32_16x16x32_bf16 v[28:31], v[152:155], v[196:199], v[28:31]
	v_mfma_f32_16x16x32_bf16 v[24:27], v[160:163], v[196:199], v[24:27]
	v_mfma_f32_16x16x32_bf16 v[12:15], v[152:155], v[204:207], v[12:15]
	v_mfma_f32_16x16x32_bf16 v[8:11], v[160:163], v[204:207], v[8:11]
	v_mfma_f32_16x16x32_bf16 v[54:57], v[208:211], v[172:175], v[54:57]
	v_mfma_f32_16x16x32_bf16 v[50:53], v[216:219], v[172:175], v[50:53]
	v_mfma_f32_16x16x32_bf16 v[38:41], v[208:211], v[184:187], v[38:41]
	v_mfma_f32_16x16x32_bf16 v[34:37], v[216:219], v[184:187], v[34:37]
	v_mfma_f32_16x16x32_bf16 v[20:23], v[208:211], v[192:195], v[20:23]
	v_mfma_f32_16x16x32_bf16 v[16:19], v[216:219], v[192:195], v[16:19]
	v_mfma_f32_16x16x32_bf16 v[4:7], v[208:211], v[200:203], v[4:7]
	v_mfma_f32_16x16x32_bf16 v[0:3], v[216:219], v[200:203], v[0:3]
	v_mfma_f32_16x16x32_bf16 v[54:57], v[212:215], v[180:183], v[54:57]
	v_mfma_f32_16x16x32_bf16 v[50:53], v[220:223], v[180:183], v[50:53]
	v_mfma_f32_16x16x32_bf16 v[38:41], v[212:215], v[188:191], v[38:41]
	v_mfma_f32_16x16x32_bf16 v[34:37], v[220:223], v[188:191], v[34:37]
	v_mfma_f32_16x16x32_bf16 v[20:23], v[212:215], v[196:199], v[20:23]
	v_mfma_f32_16x16x32_bf16 v[16:19], v[220:223], v[196:199], v[16:19]
	v_mfma_f32_16x16x32_bf16 v[4:7], v[212:215], v[204:207], v[4:7]
	v_mfma_f32_16x16x32_bf16 v[0:3], v[220:223], v[204:207], v[0:3]
	s_setprio 0
	s_add_i32 s21, 0, 0x18000
	v_add_u32_e32 v143, s21, v167
	s_barrier
	ds_read_b128 v[148:151], v143
	ds_read_b128 v[152:155], v143 offset:1024
	ds_read_b128 v[156:159], v143 offset:2048
	ds_read_b128 v[160:163], v143 offset:3072
	s_add_u32 s10, s10, 0x80000
	s_addc_u32 s11, s11, 0
	s_add_i32 s22, 0, 0x1c000
	v_add_u32_e32 v143, s22, v167
	ds_read_b128 v[208:211], v143
	ds_read_b128 v[212:215], v143 offset:1024
	ds_read_b128 v[216:219], v143 offset:2048
	ds_read_b128 v[220:223], v143 offset:3072
	s_mov_b32 m0, s42
	s_nop 0
	global_load_lds_dwordx4 v136, s[10:11]
	ds_read_b128 v[172:175], v171 offset:32768
	ds_read_b128 v[180:183], v171 offset:33792
	ds_read_b128 v[184:187], v171 offset:34816
	ds_read_b128 v[188:191], v171 offset:35840
	ds_read_b128 v[192:195], v171 offset:36864
	ds_read_b128 v[196:199], v171 offset:37888
	ds_read_b128 v[200:203], v171 offset:38912
	ds_read_b128 v[204:207], v171 offset:39936
	s_mov_b32 m0, s43
	s_nop 0
	global_load_lds_dwordx4 v132, s[10:11]
	s_waitcnt lgkmcnt(0)
	s_barrier
	s_setprio 1
	v_mfma_f32_16x16x32_bf16 v[126:129], v[148:151], v[172:175], v[126:129]
	v_mfma_f32_16x16x32_bf16 v[122:125], v[156:159], v[172:175], v[122:125]
	v_mfma_f32_16x16x32_bf16 v[110:113], v[148:151], v[184:187], v[110:113]
	v_mfma_f32_16x16x32_bf16 v[106:109], v[156:159], v[184:187], v[106:109]
	v_mfma_f32_16x16x32_bf16 v[94:97], v[148:151], v[192:195], v[94:97]
	v_mfma_f32_16x16x32_bf16 v[90:93], v[156:159], v[192:195], v[90:93]
	v_mfma_f32_16x16x32_bf16 v[78:81], v[148:151], v[200:203], v[78:81]
	v_mfma_f32_16x16x32_bf16 v[74:77], v[156:159], v[200:203], v[74:77]
	v_mfma_f32_16x16x32_bf16 v[126:129], v[152:155], v[180:183], v[126:129]
	v_mfma_f32_16x16x32_bf16 v[122:125], v[160:163], v[180:183], v[122:125]
	v_mfma_f32_16x16x32_bf16 v[110:113], v[152:155], v[188:191], v[110:113]
	v_mfma_f32_16x16x32_bf16 v[106:109], v[160:163], v[188:191], v[106:109]
	v_mfma_f32_16x16x32_bf16 v[94:97], v[152:155], v[196:199], v[94:97]
	v_mfma_f32_16x16x32_bf16 v[90:93], v[160:163], v[196:199], v[90:93]
	v_mfma_f32_16x16x32_bf16 v[78:81], v[152:155], v[204:207], v[78:81]
	v_mfma_f32_16x16x32_bf16 v[74:77], v[160:163], v[204:207], v[74:77]
	v_mfma_f32_16x16x32_bf16 v[118:121], v[208:211], v[172:175], v[118:121]
	v_mfma_f32_16x16x32_bf16 v[114:117], v[216:219], v[172:175], v[114:117]
	v_mfma_f32_16x16x32_bf16 v[102:105], v[208:211], v[184:187], v[102:105]
	v_mfma_f32_16x16x32_bf16 v[98:101], v[216:219], v[184:187], v[98:101]
	v_mfma_f32_16x16x32_bf16 v[86:89], v[208:211], v[192:195], v[86:89]
	v_mfma_f32_16x16x32_bf16 v[82:85], v[216:219], v[192:195], v[82:85]
	v_mfma_f32_16x16x32_bf16 v[70:73], v[208:211], v[200:203], v[70:73]
	v_mfma_f32_16x16x32_bf16 v[66:69], v[216:219], v[200:203], v[66:69]
	v_mfma_f32_16x16x32_bf16 v[118:121], v[212:215], v[180:183], v[118:121]
	v_mfma_f32_16x16x32_bf16 v[114:117], v[220:223], v[180:183], v[114:117]
	v_mfma_f32_16x16x32_bf16 v[102:105], v[212:215], v[188:191], v[102:105]
	v_mfma_f32_16x16x32_bf16 v[98:101], v[220:223], v[188:191], v[98:101]
	v_mfma_f32_16x16x32_bf16 v[86:89], v[212:215], v[196:199], v[86:89]
	v_mfma_f32_16x16x32_bf16 v[82:85], v[220:223], v[196:199], v[82:85]
	v_mfma_f32_16x16x32_bf16 v[70:73], v[212:215], v[204:207], v[70:73]
	v_mfma_f32_16x16x32_bf16 v[66:69], v[220:223], v[204:207], v[66:69]
	s_setprio 0
	s_barrier
	ds_read_b128 v[172:175], v171 offset:49152
	ds_read_b128 v[180:183], v171 offset:50176
	ds_read_b128 v[184:187], v171 offset:51200
	ds_read_b128 v[188:191], v171 offset:52224
	ds_read_b128 v[192:195], v171 offset:53248
	ds_read_b128 v[196:199], v171 offset:54272
	ds_read_b128 v[200:203], v171 offset:55296
	ds_read_b128 v[204:207], v171 offset:56320
	s_add_i32 s11, s21, s39
	v_lshl_add_u64 v[164:165], v[164:165], 0, s[88:89]
	s_mov_b32 m0, s11
	s_nop 0
	global_load_lds_dwordx4 v[164:165], off
	v_lshl_add_u64 v[164:165], v[176:177], 0, s[88:89]
	s_add_i32 m0, s11, 0x2000
	s_nop 0
	global_load_lds_dwordx4 v[164:165], off
	s_mov_b32 m0, s46
	v_lshl_add_u64 v[164:165], v[224:225], 0, s[88:89]
	s_nop 0
	global_load_lds_dwordx4 v[164:165], off
	v_lshl_add_u64 v[164:165], v[236:237], 0, s[88:89]
	s_mov_b32 m0, s47
	s_nop 0
	global_load_lds_dwordx4 v[164:165], off
	s_add_u32 s8, s8, 0x80080
	s_addc_u32 s9, s9, 0
	s_add_i32 s10, s39, 0x1c000
	s_mov_b32 m0, s10
	s_nop 0
	global_load_lds_dwordx4 v134, s[8:9]
	s_add_i32 m0, s10, 0x2000
	s_nop 0
	global_load_lds_dwordx4 v130, s[8:9]
	s_waitcnt vmcnt(6)
	s_waitcnt lgkmcnt(0)
	s_barrier
	s_setprio 1
	v_mfma_f32_16x16x32_bf16 v[62:65], v[148:151], v[172:175], v[62:65]
	v_mfma_f32_16x16x32_bf16 v[58:61], v[156:159], v[172:175], v[58:61]
	v_mfma_f32_16x16x32_bf16 v[46:49], v[148:151], v[184:187], v[46:49]
	v_mfma_f32_16x16x32_bf16 v[42:45], v[156:159], v[184:187], v[42:45]
	v_mfma_f32_16x16x32_bf16 v[28:31], v[148:151], v[192:195], v[28:31]
	v_mfma_f32_16x16x32_bf16 v[24:27], v[156:159], v[192:195], v[24:27]
	v_mfma_f32_16x16x32_bf16 v[12:15], v[148:151], v[200:203], v[12:15]
	v_mfma_f32_16x16x32_bf16 v[8:11], v[156:159], v[200:203], v[8:11]
	v_mfma_f32_16x16x32_bf16 v[62:65], v[152:155], v[180:183], v[62:65]
	v_mfma_f32_16x16x32_bf16 v[58:61], v[160:163], v[180:183], v[58:61]
	v_mfma_f32_16x16x32_bf16 v[46:49], v[152:155], v[188:191], v[46:49]
	v_mfma_f32_16x16x32_bf16 v[42:45], v[160:163], v[188:191], v[42:45]
	v_mfma_f32_16x16x32_bf16 v[28:31], v[152:155], v[196:199], v[28:31]
	v_mfma_f32_16x16x32_bf16 v[24:27], v[160:163], v[196:199], v[24:27]
	v_mfma_f32_16x16x32_bf16 v[12:15], v[152:155], v[204:207], v[12:15]
	v_mfma_f32_16x16x32_bf16 v[8:11], v[160:163], v[204:207], v[8:11]
	v_mfma_f32_16x16x32_bf16 v[54:57], v[208:211], v[172:175], v[54:57]
	v_mfma_f32_16x16x32_bf16 v[50:53], v[216:219], v[172:175], v[50:53]
	v_mfma_f32_16x16x32_bf16 v[38:41], v[208:211], v[184:187], v[38:41]
	v_mfma_f32_16x16x32_bf16 v[34:37], v[216:219], v[184:187], v[34:37]
	v_mfma_f32_16x16x32_bf16 v[20:23], v[208:211], v[192:195], v[20:23]
	v_mfma_f32_16x16x32_bf16 v[16:19], v[216:219], v[192:195], v[16:19]
	v_mfma_f32_16x16x32_bf16 v[4:7], v[208:211], v[200:203], v[4:7]
	v_mfma_f32_16x16x32_bf16 v[0:3], v[216:219], v[200:203], v[0:3]
	v_mfma_f32_16x16x32_bf16 v[54:57], v[212:215], v[180:183], v[54:57]
	v_mfma_f32_16x16x32_bf16 v[50:53], v[220:223], v[180:183], v[50:53]
	v_mfma_f32_16x16x32_bf16 v[38:41], v[212:215], v[188:191], v[38:41]
	v_mfma_f32_16x16x32_bf16 v[34:37], v[220:223], v[188:191], v[34:37]
	v_mfma_f32_16x16x32_bf16 v[20:23], v[212:215], v[196:199], v[20:23]
	v_mfma_f32_16x16x32_bf16 v[16:19], v[220:223], v[196:199], v[16:19]
	v_mfma_f32_16x16x32_bf16 v[4:7], v[212:215], v[204:207], v[4:7]
	v_mfma_f32_16x16x32_bf16 v[0:3], v[220:223], v[204:207], v[0:3]
	s_setprio 0
	s_add_i32 s20, s20, 2
	s_add_u32 s6, s6, 0x100
	s_addc_u32 s7, s7, 0
	s_add_u32 s13, s13, 0x100
	s_addc_u32 s15, s15, 0
	s_cmp_gt_u32 s20, 29
	s_barrier
	s_cbranch_scc0 .LBB0_372
	s_sub_i32 s6, s51, 8
	s_cmp_lt_u32 s6, 8
	s_cbranch_scc1 .Lmain_old
	s_sub_i32 s6, s51, 32
	s_cmp_lt_u32 s6, 12
	s_cbranch_scc1 .Lmain_kv
	v_mbcnt_lo_u32_b32 v226, -1, 0
	v_mbcnt_hi_u32_b32 v226, -1, v226
	v_lshrrev_b32_e32 v148, 4, v226
	v_bfe_u32 v149, v226, 2, 2
	v_and_b32_e32 v150, 3, v226
	v_lshl_add_u32 v235, v148, 2, v149
	v_lshl_add_u32 v226, v150, 4, v235
	v_lshlrev_b32_e32 v226, 2, v226
	v_add_u32_e32 v235, s45, v235
	v_lshlrev_b32_e32 v150, 4, v150
	s_lshl_b32 s6, s44, 6
	v_add_u32_e32 v150, s6, v150
	s_cmp_ge_u32 s51, 0x44
	s_cbranch_scc1 .Lmain_sig
	s_sub_i32 s6, s51, 44
	s_mov_b32 s7, 0x25e51000
	s_mov_b32 s13, 0x15e51000
	s_cmp_lt_i32 s6, 0
	s_cselect_b32 s6, s51, s6
	s_cselect_b32 s7, s13, s7
	s_lshr_b32 s13, s6, 3
	s_lshl_b32 s13, s13, 26
	s_add_i32 s7, s7, s13
	s_and_b32 s6, s6, 7
	s_lshl_b32 s6, s6, 9
	s_add_i32 s7, s7, s6
	s_lshl_b32 s6, s31, 20
	s_add_i32 s7, s7, s6
	s_add_u32 s22, s76, s7
	s_addc_u32 s23, s77, 0
	v_lshl_add_u32 v235, v235, 12, v150
	s_lshr_b32 s6, s51, 3
	s_cmp_eq_u32 s6, 3
	s_cbranch_scc1 .Lmain_q
	s_add_u32 s10, s22, 0
	s_addc_u32 s11, s23, 0
	v_cvt_pk_bf16_f32 v148, v126, v127
	v_cvt_pk_bf16_f32 v149, v128, v129
	v_cvt_pk_bf16_f32 v150, v122, v123
	v_cvt_pk_bf16_f32 v151, v124, v125
	ds_bpermute_b32 v172, v226, v148
	ds_bpermute_b32 v173, v226, v149
	ds_bpermute_b32 v174, v226, v150
	ds_bpermute_b32 v175, v226, v151
	v_cvt_pk_bf16_f32 v152, v118, v119
	v_cvt_pk_bf16_f32 v153, v120, v121
	v_cvt_pk_bf16_f32 v154, v114, v115
	v_cvt_pk_bf16_f32 v155, v116, v117
	ds_bpermute_b32 v180, v226, v152
	ds_bpermute_b32 v181, v226, v153
	ds_bpermute_b32 v182, v226, v154
	ds_bpermute_b32 v183, v226, v155
	s_add_u32 s20, s22, 0x10000
	s_addc_u32 s21, s23, 0
	v_cvt_pk_bf16_f32 v156, v110, v111
	v_cvt_pk_bf16_f32 v157, v112, v113
	v_cvt_pk_bf16_f32 v158, v106, v107
	v_cvt_pk_bf16_f32 v159, v108, v109
	ds_bpermute_b32 v184, v226, v156
	ds_bpermute_b32 v185, v226, v157
	ds_bpermute_b32 v186, v226, v158
	ds_bpermute_b32 v187, v226, v159
	v_cvt_pk_bf16_f32 v160, v102, v103
	v_cvt_pk_bf16_f32 v161, v104, v105
	v_cvt_pk_bf16_f32 v162, v98, v99
	v_cvt_pk_bf16_f32 v163, v100, v101
	ds_bpermute_b32 v188, v226, v160
	ds_bpermute_b32 v189, v226, v161
	ds_bpermute_b32 v190, v226, v162
	ds_bpermute_b32 v191, v226, v163
	s_waitcnt lgkmcnt(0)
	global_store_dwordx4 v235, v[172:175], s[10:11] sc0 sc1
	global_store_dwordx4 v235, v[180:183], s[10:11] offset:256 sc0 sc1
	global_store_dwordx4 v235, v[184:187], s[20:21] sc0 sc1
	global_store_dwordx4 v235, v[188:191], s[20:21] offset:256 sc0 sc1
	s_add_u32 s10, s22, 0x20000
	s_addc_u32 s11, s23, 0
	v_cvt_pk_bf16_f32 v148, v94, v95
	v_cvt_pk_bf16_f32 v149, v96, v97
	v_cvt_pk_bf16_f32 v150, v90, v91
	v_cvt_pk_bf16_f32 v151, v92, v93
	ds_bpermute_b32 v192, v226, v148
	ds_bpermute_b32 v193, v226, v149
	ds_bpermute_b32 v194, v226, v150
	ds_bpermute_b32 v195, v226, v151
	v_cvt_pk_bf16_f32 v152, v86, v87
	v_cvt_pk_bf16_f32 v153, v88, v89
	v_cvt_pk_bf16_f32 v154, v82, v83
	v_cvt_pk_bf16_f32 v155, v84, v85
	ds_bpermute_b32 v196, v226, v152
	ds_bpermute_b32 v197, v226, v153
	ds_bpermute_b32 v198, v226, v154
	ds_bpermute_b32 v199, v226, v155
	s_add_u32 s20, s22, 0x30000
	s_addc_u32 s21, s23, 0
	v_cvt_pk_bf16_f32 v156, v78, v79
	v_cvt_pk_bf16_f32 v157, v80, v81
	v_cvt_pk_bf16_f32 v158, v74, v75
	v_cvt_pk_bf16_f32 v159, v76, v77
	ds_bpermute_b32 v200, v226, v156
	ds_bpermute_b32 v201, v226, v157
	ds_bpermute_b32 v202, v226, v158
	ds_bpermute_b32 v203, v226, v159
	v_cvt_pk_bf16_f32 v160, v70, v71
	v_cvt_pk_bf16_f32 v161, v72, v73
	v_cvt_pk_bf16_f32 v162, v66, v67
	v_cvt_pk_bf16_f32 v163, v68, v69
	ds_bpermute_b32 v204, v226, v160
	ds_bpermute_b32 v205, v226, v161
	ds_bpermute_b32 v206, v226, v162
	ds_bpermute_b32 v207, v226, v163
	s_waitcnt lgkmcnt(0)
	global_store_dwordx4 v235, v[192:195], s[10:11] sc0 sc1
	global_store_dwordx4 v235, v[196:199], s[10:11] offset:256 sc0 sc1
	global_store_dwordx4 v235, v[200:203], s[20:21] sc0 sc1
	global_store_dwordx4 v235, v[204:207], s[20:21] offset:256 sc0 sc1
	s_add_u32 s10, s22, 0x80000
	s_addc_u32 s11, s23, 0
	v_cvt_pk_bf16_f32 v148, v62, v63
	v_cvt_pk_bf16_f32 v149, v64, v65
	v_cvt_pk_bf16_f32 v150, v58, v59
	v_cvt_pk_bf16_f32 v151, v60, v61
	ds_bpermute_b32 v208, v226, v148
	ds_bpermute_b32 v209, v226, v149
	ds_bpermute_b32 v210, v226, v150
	ds_bpermute_b32 v211, v226, v151
	v_cvt_pk_bf16_f32 v152, v54, v55
	v_cvt_pk_bf16_f32 v153, v56, v57
	v_cvt_pk_bf16_f32 v154, v50, v51
	v_cvt_pk_bf16_f32 v155, v52, v53
	ds_bpermute_b32 v212, v226, v152
	ds_bpermute_b32 v213, v226, v153
	ds_bpermute_b32 v214, v226, v154
	ds_bpermute_b32 v215, v226, v155
	s_add_u32 s20, s22, 0x90000
	s_addc_u32 s21, s23, 0
	v_cvt_pk_bf16_f32 v156, v46, v47
	v_cvt_pk_bf16_f32 v157, v48, v49
	v_cvt_pk_bf16_f32 v158, v42, v43
	v_cvt_pk_bf16_f32 v159, v44, v45
	ds_bpermute_b32 v216, v226, v156
	ds_bpermute_b32 v217, v226, v157
	ds_bpermute_b32 v218, v226, v158
	ds_bpermute_b32 v219, v226, v159
	v_cvt_pk_bf16_f32 v160, v38, v39
	v_cvt_pk_bf16_f32 v161, v40, v41
	v_cvt_pk_bf16_f32 v162, v34, v35
	v_cvt_pk_bf16_f32 v163, v36, v37
	ds_bpermute_b32 v220, v226, v160
	ds_bpermute_b32 v221, v226, v161
	ds_bpermute_b32 v222, v226, v162
	ds_bpermute_b32 v223, v226, v163
	s_waitcnt lgkmcnt(0)
	global_store_dwordx4 v235, v[208:211], s[10:11] sc0 sc1
	global_store_dwordx4 v235, v[212:215], s[10:11] offset:256 sc0 sc1
	global_store_dwordx4 v235, v[216:219], s[20:21] sc0 sc1
	global_store_dwordx4 v235, v[220:223], s[20:21] offset:256 sc0 sc1
	s_add_u32 s10, s22, 0xa0000
	s_addc_u32 s11, s23, 0
	v_cvt_pk_bf16_f32 v148, v28, v29
	v_cvt_pk_bf16_f32 v149, v30, v31
	v_cvt_pk_bf16_f32 v150, v24, v25
	v_cvt_pk_bf16_f32 v151, v26, v27
	ds_bpermute_b32 v238, v226, v148
	ds_bpermute_b32 v239, v226, v149
	ds_bpermute_b32 v240, v226, v150
	ds_bpermute_b32 v241, v226, v151
	v_cvt_pk_bf16_f32 v152, v20, v21
	v_cvt_pk_bf16_f32 v153, v22, v23
	v_cvt_pk_bf16_f32 v154, v16, v17
	v_cvt_pk_bf16_f32 v155, v18, v19
	ds_bpermute_b32 v242, v226, v152
	ds_bpermute_b32 v243, v226, v153
	ds_bpermute_b32 v244, v226, v154
	ds_bpermute_b32 v245, v226, v155
	s_add_u32 s20, s22, 0xb0000
	s_addc_u32 s21, s23, 0
	v_cvt_pk_bf16_f32 v156, v12, v13
	v_cvt_pk_bf16_f32 v157, v14, v15
	v_cvt_pk_bf16_f32 v158, v8, v9
	v_cvt_pk_bf16_f32 v159, v10, v11
	ds_bpermute_b32 v246, v226, v156
	ds_bpermute_b32 v247, v226, v157
	ds_bpermute_b32 v248, v226, v158
	ds_bpermute_b32 v249, v226, v159
	v_cvt_pk_bf16_f32 v160, v4, v5
	v_cvt_pk_bf16_f32 v161, v6, v7
	v_cvt_pk_bf16_f32 v162, v0, v1
	v_cvt_pk_bf16_f32 v163, v2, v3
	ds_bpermute_b32 v250, v226, v160
	ds_bpermute_b32 v251, v226, v161
	ds_bpermute_b32 v252, v226, v162
	ds_bpermute_b32 v253, v226, v163
	s_waitcnt lgkmcnt(0)
	global_store_dwordx4 v235, v[238:241], s[10:11] sc0 sc1
	global_store_dwordx4 v235, v[242:245], s[10:11] offset:256 sc0 sc1
	global_store_dwordx4 v235, v[246:249], s[20:21] sc0 sc1
	global_store_dwordx4 v235, v[250:253], s[20:21] offset:256 sc0 sc1
	s_branch .Lmain_latch_fast
.Lmain_q:
	s_mov_b32 s6, 0x3e0293ee
	s_add_u32 s10, s22, 0
	s_addc_u32 s11, s23, 0
	v_pk_mul_f32 v[126:127], v[126:127], s[6:7] op_sel_hi:[1,0]
	v_pk_mul_f32 v[128:129], v[128:129], s[6:7] op_sel_hi:[1,0]
	v_pk_mul_f32 v[122:123], v[122:123], s[6:7] op_sel_hi:[1,0]
	v_pk_mul_f32 v[124:125], v[124:125], s[6:7] op_sel_hi:[1,0]
	v_cvt_pk_bf16_f32 v148, v126, v127
	v_cvt_pk_bf16_f32 v149, v128, v129
	v_cvt_pk_bf16_f32 v150, v122, v123
	v_cvt_pk_bf16_f32 v151, v124, v125
	ds_bpermute_b32 v172, v226, v148
	ds_bpermute_b32 v173, v226, v149
	ds_bpermute_b32 v174, v226, v150
	ds_bpermute_b32 v175, v226, v151
	v_pk_mul_f32 v[118:119], v[118:119], s[6:7] op_sel_hi:[1,0]
	v_pk_mul_f32 v[120:121], v[120:121], s[6:7] op_sel_hi:[1,0]
	v_pk_mul_f32 v[114:115], v[114:115], s[6:7] op_sel_hi:[1,0]
	v_pk_mul_f32 v[116:117], v[116:117], s[6:7] op_sel_hi:[1,0]
	v_cvt_pk_bf16_f32 v152, v118, v119
	v_cvt_pk_bf16_f32 v153, v120, v121
	v_cvt_pk_bf16_f32 v154, v114, v115
	v_cvt_pk_bf16_f32 v155, v116, v117
	ds_bpermute_b32 v180, v226, v152
	ds_bpermute_b32 v181, v226, v153
	ds_bpermute_b32 v182, v226, v154
	ds_bpermute_b32 v183, v226, v155
	s_add_u32 s20, s22, 0x10000
	s_addc_u32 s21, s23, 0
	v_pk_mul_f32 v[110:111], v[110:111], s[6:7] op_sel_hi:[1,0]
	v_pk_mul_f32 v[112:113], v[112:113], s[6:7] op_sel_hi:[1,0]
	v_pk_mul_f32 v[106:107], v[106:107], s[6:7] op_sel_hi:[1,0]
	v_pk_mul_f32 v[108:109], v[108:109], s[6:7] op_sel_hi:[1,0]
	v_cvt_pk_bf16_f32 v156, v110, v111
	v_cvt_pk_bf16_f32 v157, v112, v113
	v_cvt_pk_bf16_f32 v158, v106, v107
	v_cvt_pk_bf16_f32 v159, v108, v109
	ds_bpermute_b32 v184, v226, v156
	ds_bpermute_b32 v185, v226, v157
	ds_bpermute_b32 v186, v226, v158
	ds_bpermute_b32 v187, v226, v159
	v_pk_mul_f32 v[102:103], v[102:103], s[6:7] op_sel_hi:[1,0]
	v_pk_mul_f32 v[104:105], v[104:105], s[6:7] op_sel_hi:[1,0]
	v_pk_mul_f32 v[98:99], v[98:99], s[6:7] op_sel_hi:[1,0]
	v_pk_mul_f32 v[100:101], v[100:101], s[6:7] op_sel_hi:[1,0]
	v_cvt_pk_bf16_f32 v160, v102, v103
	v_cvt_pk_bf16_f32 v161, v104, v105
	v_cvt_pk_bf16_f32 v162, v98, v99
	v_cvt_pk_bf16_f32 v163, v100, v101
	ds_bpermute_b32 v188, v226, v160
	ds_bpermute_b32 v189, v226, v161
	ds_bpermute_b32 v190, v226, v162
	ds_bpermute_b32 v191, v226, v163
	s_waitcnt lgkmcnt(0)
	global_store_dwordx4 v235, v[172:175], s[10:11] sc0 sc1
	global_store_dwordx4 v235, v[180:183], s[10:11] offset:256 sc0 sc1
	global_store_dwordx4 v235, v[184:187], s[20:21] sc0 sc1
	global_store_dwordx4 v235, v[188:191], s[20:21] offset:256 sc0 sc1
	s_add_u32 s10, s22, 0x20000
	s_addc_u32 s11, s23, 0
	v_pk_mul_f32 v[94:95], v[94:95], s[6:7] op_sel_hi:[1,0]
	v_pk_mul_f32 v[96:97], v[96:97], s[6:7] op_sel_hi:[1,0]
	v_pk_mul_f32 v[90:91], v[90:91], s[6:7] op_sel_hi:[1,0]
	v_pk_mul_f32 v[92:93], v[92:93], s[6:7] op_sel_hi:[1,0]
	v_cvt_pk_bf16_f32 v148, v94, v95
	v_cvt_pk_bf16_f32 v149, v96, v97
	v_cvt_pk_bf16_f32 v150, v90, v91
	v_cvt_pk_bf16_f32 v151, v92, v93
	ds_bpermute_b32 v192, v226, v148
	ds_bpermute_b32 v193, v226, v149
	ds_bpermute_b32 v194, v226, v150
	ds_bpermute_b32 v195, v226, v151
	v_pk_mul_f32 v[86:87], v[86:87], s[6:7] op_sel_hi:[1,0]
	v_pk_mul_f32 v[88:89], v[88:89], s[6:7] op_sel_hi:[1,0]
	v_pk_mul_f32 v[82:83], v[82:83], s[6:7] op_sel_hi:[1,0]
	v_pk_mul_f32 v[84:85], v[84:85], s[6:7] op_sel_hi:[1,0]
	v_cvt_pk_bf16_f32 v152, v86, v87
	v_cvt_pk_bf16_f32 v153, v88, v89
	v_cvt_pk_bf16_f32 v154, v82, v83
	v_cvt_pk_bf16_f32 v155, v84, v85
	ds_bpermute_b32 v196, v226, v152
	ds_bpermute_b32 v197, v226, v153
	ds_bpermute_b32 v198, v226, v154
	ds_bpermute_b32 v199, v226, v155
	s_add_u32 s20, s22, 0x30000
	s_addc_u32 s21, s23, 0
	v_pk_mul_f32 v[78:79], v[78:79], s[6:7] op_sel_hi:[1,0]
	v_pk_mul_f32 v[80:81], v[80:81], s[6:7] op_sel_hi:[1,0]
	v_pk_mul_f32 v[74:75], v[74:75], s[6:7] op_sel_hi:[1,0]
	v_pk_mul_f32 v[76:77], v[76:77], s[6:7] op_sel_hi:[1,0]
	v_cvt_pk_bf16_f32 v156, v78, v79
	v_cvt_pk_bf16_f32 v157, v80, v81
	v_cvt_pk_bf16_f32 v158, v74, v75
	v_cvt_pk_bf16_f32 v159, v76, v77
	ds_bpermute_b32 v200, v226, v156
	ds_bpermute_b32 v201, v226, v157
	ds_bpermute_b32 v202, v226, v158
	ds_bpermute_b32 v203, v226, v159
	v_pk_mul_f32 v[70:71], v[70:71], s[6:7] op_sel_hi:[1,0]
	v_pk_mul_f32 v[72:73], v[72:73], s[6:7] op_sel_hi:[1,0]
	v_pk_mul_f32 v[66:67], v[66:67], s[6:7] op_sel_hi:[1,0]
	v_pk_mul_f32 v[68:69], v[68:69], s[6:7] op_sel_hi:[1,0]
	v_cvt_pk_bf16_f32 v160, v70, v71
	v_cvt_pk_bf16_f32 v161, v72, v73
	v_cvt_pk_bf16_f32 v162, v66, v67
	v_cvt_pk_bf16_f32 v163, v68, v69
	ds_bpermute_b32 v204, v226, v160
	ds_bpermute_b32 v205, v226, v161
	ds_bpermute_b32 v206, v226, v162
	ds_bpermute_b32 v207, v226, v163
	s_waitcnt lgkmcnt(0)
	global_store_dwordx4 v235, v[192:195], s[10:11] sc0 sc1
	global_store_dwordx4 v235, v[196:199], s[10:11] offset:256 sc0 sc1
	global_store_dwordx4 v235, v[200:203], s[20:21] sc0 sc1
	global_store_dwordx4 v235, v[204:207], s[20:21] offset:256 sc0 sc1
	s_add_u32 s10, s22, 0x80000
	s_addc_u32 s11, s23, 0
	v_pk_mul_f32 v[62:63], v[62:63], s[6:7] op_sel_hi:[1,0]
	v_pk_mul_f32 v[64:65], v[64:65], s[6:7] op_sel_hi:[1,0]
	v_pk_mul_f32 v[58:59], v[58:59], s[6:7] op_sel_hi:[1,0]
	v_pk_mul_f32 v[60:61], v[60:61], s[6:7] op_sel_hi:[1,0]
	v_cvt_pk_bf16_f32 v148, v62, v63
	v_cvt_pk_bf16_f32 v149, v64, v65
	v_cvt_pk_bf16_f32 v150, v58, v59
	v_cvt_pk_bf16_f32 v151, v60, v61
	ds_bpermute_b32 v208, v226, v148
	ds_bpermute_b32 v209, v226, v149
	ds_bpermute_b32 v210, v226, v150
	ds_bpermute_b32 v211, v226, v151
	v_pk_mul_f32 v[54:55], v[54:55], s[6:7] op_sel_hi:[1,0]
	v_pk_mul_f32 v[56:57], v[56:57], s[6:7] op_sel_hi:[1,0]
	v_pk_mul_f32 v[50:51], v[50:51], s[6:7] op_sel_hi:[1,0]
	v_pk_mul_f32 v[52:53], v[52:53], s[6:7] op_sel_hi:[1,0]
	v_cvt_pk_bf16_f32 v152, v54, v55
	v_cvt_pk_bf16_f32 v153, v56, v57
	v_cvt_pk_bf16_f32 v154, v50, v51
	v_cvt_pk_bf16_f32 v155, v52, v53
	ds_bpermute_b32 v212, v226, v152
	ds_bpermute_b32 v213, v226, v153
	ds_bpermute_b32 v214, v226, v154
	ds_bpermute_b32 v215, v226, v155
	s_add_u32 s20, s22, 0x90000
	s_addc_u32 s21, s23, 0
	v_pk_mul_f32 v[46:47], v[46:47], s[6:7] op_sel_hi:[1,0]
	v_pk_mul_f32 v[48:49], v[48:49], s[6:7] op_sel_hi:[1,0]
	v_pk_mul_f32 v[42:43], v[42:43], s[6:7] op_sel_hi:[1,0]
	v_pk_mul_f32 v[44:45], v[44:45], s[6:7] op_sel_hi:[1,0]
	v_cvt_pk_bf16_f32 v156, v46, v47
	v_cvt_pk_bf16_f32 v157, v48, v49
	v_cvt_pk_bf16_f32 v158, v42, v43
	v_cvt_pk_bf16_f32 v159, v44, v45
	ds_bpermute_b32 v216, v226, v156
	ds_bpermute_b32 v217, v226, v157
	ds_bpermute_b32 v218, v226, v158
	ds_bpermute_b32 v219, v226, v159
	v_pk_mul_f32 v[38:39], v[38:39], s[6:7] op_sel_hi:[1,0]
	v_pk_mul_f32 v[40:41], v[40:41], s[6:7] op_sel_hi:[1,0]
	v_pk_mul_f32 v[34:35], v[34:35], s[6:7] op_sel_hi:[1,0]
	v_pk_mul_f32 v[36:37], v[36:37], s[6:7] op_sel_hi:[1,0]
	v_cvt_pk_bf16_f32 v160, v38, v39
	v_cvt_pk_bf16_f32 v161, v40, v41
	v_cvt_pk_bf16_f32 v162, v34, v35
	v_cvt_pk_bf16_f32 v163, v36, v37
	ds_bpermute_b32 v220, v226, v160
	ds_bpermute_b32 v221, v226, v161
	ds_bpermute_b32 v222, v226, v162
	ds_bpermute_b32 v223, v226, v163
	s_waitcnt lgkmcnt(0)
	global_store_dwordx4 v235, v[208:211], s[10:11] sc0 sc1
	global_store_dwordx4 v235, v[212:215], s[10:11] offset:256 sc0 sc1
	global_store_dwordx4 v235, v[216:219], s[20:21] sc0 sc1
	global_store_dwordx4 v235, v[220:223], s[20:21] offset:256 sc0 sc1
	s_add_u32 s10, s22, 0xa0000
	s_addc_u32 s11, s23, 0
	v_pk_mul_f32 v[28:29], v[28:29], s[6:7] op_sel_hi:[1,0]
	v_pk_mul_f32 v[30:31], v[30:31], s[6:7] op_sel_hi:[1,0]
	v_pk_mul_f32 v[24:25], v[24:25], s[6:7] op_sel_hi:[1,0]
	v_pk_mul_f32 v[26:27], v[26:27], s[6:7] op_sel_hi:[1,0]
	v_cvt_pk_bf16_f32 v148, v28, v29
	v_cvt_pk_bf16_f32 v149, v30, v31
	v_cvt_pk_bf16_f32 v150, v24, v25
	v_cvt_pk_bf16_f32 v151, v26, v27
	ds_bpermute_b32 v238, v226, v148
	ds_bpermute_b32 v239, v226, v149
	ds_bpermute_b32 v240, v226, v150
	ds_bpermute_b32 v241, v226, v151
	v_pk_mul_f32 v[20:21], v[20:21], s[6:7] op_sel_hi:[1,0]
	v_pk_mul_f32 v[22:23], v[22:23], s[6:7] op_sel_hi:[1,0]
	v_pk_mul_f32 v[16:17], v[16:17], s[6:7] op_sel_hi:[1,0]
	v_pk_mul_f32 v[18:19], v[18:19], s[6:7] op_sel_hi:[1,0]
	v_cvt_pk_bf16_f32 v152, v20, v21
	v_cvt_pk_bf16_f32 v153, v22, v23
	v_cvt_pk_bf16_f32 v154, v16, v17
	v_cvt_pk_bf16_f32 v155, v18, v19
	ds_bpermute_b32 v242, v226, v152
	ds_bpermute_b32 v243, v226, v153
	ds_bpermute_b32 v244, v226, v154
	ds_bpermute_b32 v245, v226, v155
	s_add_u32 s20, s22, 0xb0000
	s_addc_u32 s21, s23, 0
	v_pk_mul_f32 v[12:13], v[12:13], s[6:7] op_sel_hi:[1,0]
	v_pk_mul_f32 v[14:15], v[14:15], s[6:7] op_sel_hi:[1,0]
	v_pk_mul_f32 v[8:9], v[8:9], s[6:7] op_sel_hi:[1,0]
	v_pk_mul_f32 v[10:11], v[10:11], s[6:7] op_sel_hi:[1,0]
	v_cvt_pk_bf16_f32 v156, v12, v13
	v_cvt_pk_bf16_f32 v157, v14, v15
	v_cvt_pk_bf16_f32 v158, v8, v9
	v_cvt_pk_bf16_f32 v159, v10, v11
	ds_bpermute_b32 v246, v226, v156
	ds_bpermute_b32 v247, v226, v157
	ds_bpermute_b32 v248, v226, v158
	ds_bpermute_b32 v249, v226, v159
	v_pk_mul_f32 v[4:5], v[4:5], s[6:7] op_sel_hi:[1,0]
	v_pk_mul_f32 v[6:7], v[6:7], s[6:7] op_sel_hi:[1,0]
	v_pk_mul_f32 v[0:1], v[0:1], s[6:7] op_sel_hi:[1,0]
	v_pk_mul_f32 v[2:3], v[2:3], s[6:7] op_sel_hi:[1,0]
	v_cvt_pk_bf16_f32 v160, v4, v5
	v_cvt_pk_bf16_f32 v161, v6, v7
	v_cvt_pk_bf16_f32 v162, v0, v1
	v_cvt_pk_bf16_f32 v163, v2, v3
	ds_bpermute_b32 v250, v226, v160
	ds_bpermute_b32 v251, v226, v161
	ds_bpermute_b32 v252, v226, v162
	ds_bpermute_b32 v253, v226, v163
	s_waitcnt lgkmcnt(0)
	global_store_dwordx4 v235, v[238:241], s[10:11] sc0 sc1
	global_store_dwordx4 v235, v[242:245], s[10:11] offset:256 sc0 sc1
	global_store_dwordx4 v235, v[246:249], s[20:21] sc0 sc1
	global_store_dwordx4 v235, v[250:253], s[20:21] offset:256 sc0 sc1
	s_branch .Lmain_latch_fast
.Lmain_sig:
	s_mul_i32 s7, s31, 0x300000
	s_sub_i32 s6, s51, 0x44
	s_lshl_b32 s6, s6, 9
	s_add_i32 s7, s7, s6
	s_add_i32 s7, s7, 0x37f51000
	s_add_u32 s22, s76, s7
	s_addc_u32 s23, s77, 0
	v_mul_u32_u24_e32 v235, 0x3000, v235
	v_add_u32_e32 v235, v235, v150
	s_add_u32 s10, s22, 0
	s_addc_u32 s11, s23, 0
	v_mul_f32_e32 v126, 0xbfb8aa3b, v126
	v_mul_f32_e32 v127, 0xbfb8aa3b, v127
	v_mul_f32_e32 v128, 0xbfb8aa3b, v128
	v_mul_f32_e32 v129, 0xbfb8aa3b, v129
	v_mul_f32_e32 v122, 0xbfb8aa3b, v122
	v_mul_f32_e32 v123, 0xbfb8aa3b, v123
	v_mul_f32_e32 v124, 0xbfb8aa3b, v124
	v_mul_f32_e32 v125, 0xbfb8aa3b, v125
	v_exp_f32_e32 v126, v126
	v_exp_f32_e32 v127, v127
	v_exp_f32_e32 v128, v128
	v_exp_f32_e32 v129, v129
	v_exp_f32_e32 v122, v122
	v_exp_f32_e32 v123, v123
	v_exp_f32_e32 v124, v124
	v_exp_f32_e32 v125, v125
	v_add_f32_e32 v126, 1.0, v126
	v_add_f32_e32 v127, 1.0, v127
	v_add_f32_e32 v128, 1.0, v128
	v_add_f32_e32 v129, 1.0, v129
	v_add_f32_e32 v122, 1.0, v122
	v_add_f32_e32 v123, 1.0, v123
	v_add_f32_e32 v124, 1.0, v124
	v_add_f32_e32 v125, 1.0, v125
	v_rcp_f32_e32 v126, v126
	v_rcp_f32_e32 v127, v127
	v_rcp_f32_e32 v128, v128
	v_rcp_f32_e32 v129, v129
	v_rcp_f32_e32 v122, v122
	v_rcp_f32_e32 v123, v123
	v_rcp_f32_e32 v124, v124
	v_rcp_f32_e32 v125, v125
	v_cvt_pk_bf16_f32 v148, v126, v127
	v_cvt_pk_bf16_f32 v149, v128, v129
	v_cvt_pk_bf16_f32 v150, v122, v123
	v_cvt_pk_bf16_f32 v151, v124, v125
	ds_bpermute_b32 v172, v226, v148
	ds_bpermute_b32 v173, v226, v149
	ds_bpermute_b32 v174, v226, v150
	ds_bpermute_b32 v175, v226, v151
	v_mul_f32_e32 v118, 0xbfb8aa3b, v118
	v_mul_f32_e32 v119, 0xbfb8aa3b, v119
	v_mul_f32_e32 v120, 0xbfb8aa3b, v120
	v_mul_f32_e32 v121, 0xbfb8aa3b, v121
	v_mul_f32_e32 v114, 0xbfb8aa3b, v114
	v_mul_f32_e32 v115, 0xbfb8aa3b, v115
	v_mul_f32_e32 v116, 0xbfb8aa3b, v116
	v_mul_f32_e32 v117, 0xbfb8aa3b, v117
	v_exp_f32_e32 v118, v118
	v_exp_f32_e32 v119, v119
	v_exp_f32_e32 v120, v120
	v_exp_f32_e32 v121, v121
	v_exp_f32_e32 v114, v114
	v_exp_f32_e32 v115, v115
	v_exp_f32_e32 v116, v116
	v_exp_f32_e32 v117, v117
	v_add_f32_e32 v118, 1.0, v118
	v_add_f32_e32 v119, 1.0, v119
	v_add_f32_e32 v120, 1.0, v120
	v_add_f32_e32 v121, 1.0, v121
	v_add_f32_e32 v114, 1.0, v114
	v_add_f32_e32 v115, 1.0, v115
	v_add_f32_e32 v116, 1.0, v116
	v_add_f32_e32 v117, 1.0, v117
	v_rcp_f32_e32 v118, v118
	v_rcp_f32_e32 v119, v119
	v_rcp_f32_e32 v120, v120
	v_rcp_f32_e32 v121, v121
	v_rcp_f32_e32 v114, v114
	v_rcp_f32_e32 v115, v115
	v_rcp_f32_e32 v116, v116
	v_rcp_f32_e32 v117, v117
	v_cvt_pk_bf16_f32 v152, v118, v119
	v_cvt_pk_bf16_f32 v153, v120, v121
	v_cvt_pk_bf16_f32 v154, v114, v115
	v_cvt_pk_bf16_f32 v155, v116, v117
	ds_bpermute_b32 v180, v226, v152
	ds_bpermute_b32 v181, v226, v153
	ds_bpermute_b32 v182, v226, v154
	ds_bpermute_b32 v183, v226, v155
	s_add_u32 s20, s22, 0x30000
	s_addc_u32 s21, s23, 0
	v_mul_f32_e32 v110, 0xbfb8aa3b, v110
	v_mul_f32_e32 v111, 0xbfb8aa3b, v111
	v_mul_f32_e32 v112, 0xbfb8aa3b, v112
	v_mul_f32_e32 v113, 0xbfb8aa3b, v113
	v_mul_f32_e32 v106, 0xbfb8aa3b, v106
	v_mul_f32_e32 v107, 0xbfb8aa3b, v107
	v_mul_f32_e32 v108, 0xbfb8aa3b, v108
	v_mul_f32_e32 v109, 0xbfb8aa3b, v109
	v_exp_f32_e32 v110, v110
	v_exp_f32_e32 v111, v111
	v_exp_f32_e32 v112, v112
	v_exp_f32_e32 v113, v113
	v_exp_f32_e32 v106, v106
	v_exp_f32_e32 v107, v107
	v_exp_f32_e32 v108, v108
	v_exp_f32_e32 v109, v109
	v_add_f32_e32 v110, 1.0, v110
	v_add_f32_e32 v111, 1.0, v111
	v_add_f32_e32 v112, 1.0, v112
	v_add_f32_e32 v113, 1.0, v113
	v_add_f32_e32 v106, 1.0, v106
	v_add_f32_e32 v107, 1.0, v107
	v_add_f32_e32 v108, 1.0, v108
	v_add_f32_e32 v109, 1.0, v109
	v_rcp_f32_e32 v110, v110
	v_rcp_f32_e32 v111, v111
	v_rcp_f32_e32 v112, v112
	v_rcp_f32_e32 v113, v113
	v_rcp_f32_e32 v106, v106
	v_rcp_f32_e32 v107, v107
	v_rcp_f32_e32 v108, v108
	v_rcp_f32_e32 v109, v109
	v_cvt_pk_bf16_f32 v156, v110, v111
	v_cvt_pk_bf16_f32 v157, v112, v113
	v_cvt_pk_bf16_f32 v158, v106, v107
	v_cvt_pk_bf16_f32 v159, v108, v109
	ds_bpermute_b32 v184, v226, v156
	ds_bpermute_b32 v185, v226, v157
	ds_bpermute_b32 v186, v226, v158
	ds_bpermute_b32 v187, v226, v159
	v_mul_f32_e32 v102, 0xbfb8aa3b, v102
	v_mul_f32_e32 v103, 0xbfb8aa3b, v103
	v_mul_f32_e32 v104, 0xbfb8aa3b, v104
	v_mul_f32_e32 v105, 0xbfb8aa3b, v105
	v_mul_f32_e32 v98, 0xbfb8aa3b, v98
	v_mul_f32_e32 v99, 0xbfb8aa3b, v99
	v_mul_f32_e32 v100, 0xbfb8aa3b, v100
	v_mul_f32_e32 v101, 0xbfb8aa3b, v101
	v_exp_f32_e32 v102, v102
	v_exp_f32_e32 v103, v103
	v_exp_f32_e32 v104, v104
	v_exp_f32_e32 v105, v105
	v_exp_f32_e32 v98, v98
	v_exp_f32_e32 v99, v99
	v_exp_f32_e32 v100, v100
	v_exp_f32_e32 v101, v101
	v_add_f32_e32 v102, 1.0, v102
	v_add_f32_e32 v103, 1.0, v103
	v_add_f32_e32 v104, 1.0, v104
	v_add_f32_e32 v105, 1.0, v105
	v_add_f32_e32 v98, 1.0, v98
	v_add_f32_e32 v99, 1.0, v99
	v_add_f32_e32 v100, 1.0, v100
	v_add_f32_e32 v101, 1.0, v101
	v_rcp_f32_e32 v102, v102
	v_rcp_f32_e32 v103, v103
	v_rcp_f32_e32 v104, v104
	v_rcp_f32_e32 v105, v105
	v_rcp_f32_e32 v98, v98
	v_rcp_f32_e32 v99, v99
	v_rcp_f32_e32 v100, v100
	v_rcp_f32_e32 v101, v101
	v_cvt_pk_bf16_f32 v160, v102, v103
	v_cvt_pk_bf16_f32 v161, v104, v105
	v_cvt_pk_bf16_f32 v162, v98, v99
	v_cvt_pk_bf16_f32 v163, v100, v101
	ds_bpermute_b32 v188, v226, v160
	ds_bpermute_b32 v189, v226, v161
	ds_bpermute_b32 v190, v226, v162
	ds_bpermute_b32 v191, v226, v163
	s_waitcnt lgkmcnt(0)
	global_store_dwordx4 v235, v[172:175], s[10:11] sc0 sc1
	global_store_dwordx4 v235, v[180:183], s[10:11] offset:256 sc0 sc1
	global_store_dwordx4 v235, v[184:187], s[20:21] sc0 sc1
	global_store_dwordx4 v235, v[188:191], s[20:21] offset:256 sc0 sc1
	s_add_u32 s10, s22, 0x60000
	s_addc_u32 s11, s23, 0
	v_mul_f32_e32 v94, 0xbfb8aa3b, v94
	v_mul_f32_e32 v95, 0xbfb8aa3b, v95
	v_mul_f32_e32 v96, 0xbfb8aa3b, v96
	v_mul_f32_e32 v97, 0xbfb8aa3b, v97
	v_mul_f32_e32 v90, 0xbfb8aa3b, v90
	v_mul_f32_e32 v91, 0xbfb8aa3b, v91
	v_mul_f32_e32 v92, 0xbfb8aa3b, v92
	v_mul_f32_e32 v93, 0xbfb8aa3b, v93
	v_exp_f32_e32 v94, v94
	v_exp_f32_e32 v95, v95
	v_exp_f32_e32 v96, v96
	v_exp_f32_e32 v97, v97
	v_exp_f32_e32 v90, v90
	v_exp_f32_e32 v91, v91
	v_exp_f32_e32 v92, v92
	v_exp_f32_e32 v93, v93
	v_add_f32_e32 v94, 1.0, v94
	v_add_f32_e32 v95, 1.0, v95
	v_add_f32_e32 v96, 1.0, v96
	v_add_f32_e32 v97, 1.0, v97
	v_add_f32_e32 v90, 1.0, v90
	v_add_f32_e32 v91, 1.0, v91
	v_add_f32_e32 v92, 1.0, v92
	v_add_f32_e32 v93, 1.0, v93
	v_rcp_f32_e32 v94, v94
	v_rcp_f32_e32 v95, v95
	v_rcp_f32_e32 v96, v96
	v_rcp_f32_e32 v97, v97
	v_rcp_f32_e32 v90, v90
	v_rcp_f32_e32 v91, v91
	v_rcp_f32_e32 v92, v92
	v_rcp_f32_e32 v93, v93
	v_cvt_pk_bf16_f32 v148, v94, v95
	v_cvt_pk_bf16_f32 v149, v96, v97
	v_cvt_pk_bf16_f32 v150, v90, v91
	v_cvt_pk_bf16_f32 v151, v92, v93
	ds_bpermute_b32 v192, v226, v148
	ds_bpermute_b32 v193, v226, v149
	ds_bpermute_b32 v194, v226, v150
	ds_bpermute_b32 v195, v226, v151
	v_mul_f32_e32 v86, 0xbfb8aa3b, v86
	v_mul_f32_e32 v87, 0xbfb8aa3b, v87
	v_mul_f32_e32 v88, 0xbfb8aa3b, v88
	v_mul_f32_e32 v89, 0xbfb8aa3b, v89
	v_mul_f32_e32 v82, 0xbfb8aa3b, v82
	v_mul_f32_e32 v83, 0xbfb8aa3b, v83
	v_mul_f32_e32 v84, 0xbfb8aa3b, v84
	v_mul_f32_e32 v85, 0xbfb8aa3b, v85
	v_exp_f32_e32 v86, v86
	v_exp_f32_e32 v87, v87
	v_exp_f32_e32 v88, v88
	v_exp_f32_e32 v89, v89
	v_exp_f32_e32 v82, v82
	v_exp_f32_e32 v83, v83
	v_exp_f32_e32 v84, v84
	v_exp_f32_e32 v85, v85
	v_add_f32_e32 v86, 1.0, v86
	v_add_f32_e32 v87, 1.0, v87
	v_add_f32_e32 v88, 1.0, v88
	v_add_f32_e32 v89, 1.0, v89
	v_add_f32_e32 v82, 1.0, v82
	v_add_f32_e32 v83, 1.0, v83
	v_add_f32_e32 v84, 1.0, v84
	v_add_f32_e32 v85, 1.0, v85
	v_rcp_f32_e32 v86, v86
	v_rcp_f32_e32 v87, v87
	v_rcp_f32_e32 v88, v88
	v_rcp_f32_e32 v89, v89
	v_rcp_f32_e32 v82, v82
	v_rcp_f32_e32 v83, v83
	v_rcp_f32_e32 v84, v84
	v_rcp_f32_e32 v85, v85
	v_cvt_pk_bf16_f32 v152, v86, v87
	v_cvt_pk_bf16_f32 v153, v88, v89
	v_cvt_pk_bf16_f32 v154, v82, v83
	v_cvt_pk_bf16_f32 v155, v84, v85
	ds_bpermute_b32 v196, v226, v152
	ds_bpermute_b32 v197, v226, v153
	ds_bpermute_b32 v198, v226, v154
	ds_bpermute_b32 v199, v226, v155
	s_add_u32 s20, s22, 0x90000
	s_addc_u32 s21, s23, 0
	v_mul_f32_e32 v78, 0xbfb8aa3b, v78
	v_mul_f32_e32 v79, 0xbfb8aa3b, v79
	v_mul_f32_e32 v80, 0xbfb8aa3b, v80
	v_mul_f32_e32 v81, 0xbfb8aa3b, v81
	v_mul_f32_e32 v74, 0xbfb8aa3b, v74
	v_mul_f32_e32 v75, 0xbfb8aa3b, v75
	v_mul_f32_e32 v76, 0xbfb8aa3b, v76
	v_mul_f32_e32 v77, 0xbfb8aa3b, v77
	v_exp_f32_e32 v78, v78
	v_exp_f32_e32 v79, v79
	v_exp_f32_e32 v80, v80
	v_exp_f32_e32 v81, v81
	v_exp_f32_e32 v74, v74
	v_exp_f32_e32 v75, v75
	v_exp_f32_e32 v76, v76
	v_exp_f32_e32 v77, v77
	v_add_f32_e32 v78, 1.0, v78
	v_add_f32_e32 v79, 1.0, v79
	v_add_f32_e32 v80, 1.0, v80
	v_add_f32_e32 v81, 1.0, v81
	v_add_f32_e32 v74, 1.0, v74
	v_add_f32_e32 v75, 1.0, v75
	v_add_f32_e32 v76, 1.0, v76
	v_add_f32_e32 v77, 1.0, v77
	v_rcp_f32_e32 v78, v78
	v_rcp_f32_e32 v79, v79
	v_rcp_f32_e32 v80, v80
	v_rcp_f32_e32 v81, v81
	v_rcp_f32_e32 v74, v74
	v_rcp_f32_e32 v75, v75
	v_rcp_f32_e32 v76, v76
	v_rcp_f32_e32 v77, v77
	v_cvt_pk_bf16_f32 v156, v78, v79
	v_cvt_pk_bf16_f32 v157, v80, v81
	v_cvt_pk_bf16_f32 v158, v74, v75
	v_cvt_pk_bf16_f32 v159, v76, v77
	ds_bpermute_b32 v200, v226, v156
	ds_bpermute_b32 v201, v226, v157
	ds_bpermute_b32 v202, v226, v158
	ds_bpermute_b32 v203, v226, v159
	v_mul_f32_e32 v70, 0xbfb8aa3b, v70
	v_mul_f32_e32 v71, 0xbfb8aa3b, v71
	v_mul_f32_e32 v72, 0xbfb8aa3b, v72
	v_mul_f32_e32 v73, 0xbfb8aa3b, v73
	v_mul_f32_e32 v66, 0xbfb8aa3b, v66
	v_mul_f32_e32 v67, 0xbfb8aa3b, v67
	v_mul_f32_e32 v68, 0xbfb8aa3b, v68
	v_mul_f32_e32 v69, 0xbfb8aa3b, v69
	v_exp_f32_e32 v70, v70
	v_exp_f32_e32 v71, v71
	v_exp_f32_e32 v72, v72
	v_exp_f32_e32 v73, v73
	v_exp_f32_e32 v66, v66
	v_exp_f32_e32 v67, v67
	v_exp_f32_e32 v68, v68
	v_exp_f32_e32 v69, v69
	v_add_f32_e32 v70, 1.0, v70
	v_add_f32_e32 v71, 1.0, v71
	v_add_f32_e32 v72, 1.0, v72
	v_add_f32_e32 v73, 1.0, v73
	v_add_f32_e32 v66, 1.0, v66
	v_add_f32_e32 v67, 1.0, v67
	v_add_f32_e32 v68, 1.0, v68
	v_add_f32_e32 v69, 1.0, v69
	v_rcp_f32_e32 v70, v70
	v_rcp_f32_e32 v71, v71
	v_rcp_f32_e32 v72, v72
	v_rcp_f32_e32 v73, v73
	v_rcp_f32_e32 v66, v66
	v_rcp_f32_e32 v67, v67
	v_rcp_f32_e32 v68, v68
	v_rcp_f32_e32 v69, v69
	v_cvt_pk_bf16_f32 v160, v70, v71
	v_cvt_pk_bf16_f32 v161, v72, v73
	v_cvt_pk_bf16_f32 v162, v66, v67
	v_cvt_pk_bf16_f32 v163, v68, v69
	ds_bpermute_b32 v204, v226, v160
	ds_bpermute_b32 v205, v226, v161
	ds_bpermute_b32 v206, v226, v162
	ds_bpermute_b32 v207, v226, v163
	s_waitcnt lgkmcnt(0)
	global_store_dwordx4 v235, v[192:195], s[10:11] sc0 sc1
	global_store_dwordx4 v235, v[196:199], s[10:11] offset:256 sc0 sc1
	global_store_dwordx4 v235, v[200:203], s[20:21] sc0 sc1
	global_store_dwordx4 v235, v[204:207], s[20:21] offset:256 sc0 sc1
	s_add_u32 s10, s22, 0x180000
	s_addc_u32 s11, s23, 0
	v_mul_f32_e32 v62, 0xbfb8aa3b, v62
	v_mul_f32_e32 v63, 0xbfb8aa3b, v63
	v_mul_f32_e32 v64, 0xbfb8aa3b, v64
	v_mul_f32_e32 v65, 0xbfb8aa3b, v65
	v_mul_f32_e32 v58, 0xbfb8aa3b, v58
	v_mul_f32_e32 v59, 0xbfb8aa3b, v59
	v_mul_f32_e32 v60, 0xbfb8aa3b, v60
	v_mul_f32_e32 v61, 0xbfb8aa3b, v61
	v_exp_f32_e32 v62, v62
	v_exp_f32_e32 v63, v63
	v_exp_f32_e32 v64, v64
	v_exp_f32_e32 v65, v65
	v_exp_f32_e32 v58, v58
	v_exp_f32_e32 v59, v59
	v_exp_f32_e32 v60, v60
	v_exp_f32_e32 v61, v61
	v_add_f32_e32 v62, 1.0, v62
	v_add_f32_e32 v63, 1.0, v63
	v_add_f32_e32 v64, 1.0, v64
	v_add_f32_e32 v65, 1.0, v65
	v_add_f32_e32 v58, 1.0, v58
	v_add_f32_e32 v59, 1.0, v59
	v_add_f32_e32 v60, 1.0, v60
	v_add_f32_e32 v61, 1.0, v61
	v_rcp_f32_e32 v62, v62
	v_rcp_f32_e32 v63, v63
	v_rcp_f32_e32 v64, v64
	v_rcp_f32_e32 v65, v65
	v_rcp_f32_e32 v58, v58
	v_rcp_f32_e32 v59, v59
	v_rcp_f32_e32 v60, v60
	v_rcp_f32_e32 v61, v61
	v_cvt_pk_bf16_f32 v148, v62, v63
	v_cvt_pk_bf16_f32 v149, v64, v65
	v_cvt_pk_bf16_f32 v150, v58, v59
	v_cvt_pk_bf16_f32 v151, v60, v61
	ds_bpermute_b32 v208, v226, v148
	ds_bpermute_b32 v209, v226, v149
	ds_bpermute_b32 v210, v226, v150
	ds_bpermute_b32 v211, v226, v151
	v_mul_f32_e32 v54, 0xbfb8aa3b, v54
	v_mul_f32_e32 v55, 0xbfb8aa3b, v55
	v_mul_f32_e32 v56, 0xbfb8aa3b, v56
	v_mul_f32_e32 v57, 0xbfb8aa3b, v57
	v_mul_f32_e32 v50, 0xbfb8aa3b, v50
	v_mul_f32_e32 v51, 0xbfb8aa3b, v51
	v_mul_f32_e32 v52, 0xbfb8aa3b, v52
	v_mul_f32_e32 v53, 0xbfb8aa3b, v53
	v_exp_f32_e32 v54, v54
	v_exp_f32_e32 v55, v55
	v_exp_f32_e32 v56, v56
	v_exp_f32_e32 v57, v57
	v_exp_f32_e32 v50, v50
	v_exp_f32_e32 v51, v51
	v_exp_f32_e32 v52, v52
	v_exp_f32_e32 v53, v53
	v_add_f32_e32 v54, 1.0, v54
	v_add_f32_e32 v55, 1.0, v55
	v_add_f32_e32 v56, 1.0, v56
	v_add_f32_e32 v57, 1.0, v57
	v_add_f32_e32 v50, 1.0, v50
	v_add_f32_e32 v51, 1.0, v51
	v_add_f32_e32 v52, 1.0, v52
	v_add_f32_e32 v53, 1.0, v53
	v_rcp_f32_e32 v54, v54
	v_rcp_f32_e32 v55, v55
	v_rcp_f32_e32 v56, v56
	v_rcp_f32_e32 v57, v57
	v_rcp_f32_e32 v50, v50
	v_rcp_f32_e32 v51, v51
	v_rcp_f32_e32 v52, v52
	v_rcp_f32_e32 v53, v53
	v_cvt_pk_bf16_f32 v152, v54, v55
	v_cvt_pk_bf16_f32 v153, v56, v57
	v_cvt_pk_bf16_f32 v154, v50, v51
	v_cvt_pk_bf16_f32 v155, v52, v53
	ds_bpermute_b32 v212, v226, v152
	ds_bpermute_b32 v213, v226, v153
	ds_bpermute_b32 v214, v226, v154
	ds_bpermute_b32 v215, v226, v155
	s_add_u32 s20, s22, 0x1b0000
	s_addc_u32 s21, s23, 0
	v_mul_f32_e32 v46, 0xbfb8aa3b, v46
	v_mul_f32_e32 v47, 0xbfb8aa3b, v47
	v_mul_f32_e32 v48, 0xbfb8aa3b, v48
	v_mul_f32_e32 v49, 0xbfb8aa3b, v49
	v_mul_f32_e32 v42, 0xbfb8aa3b, v42
	v_mul_f32_e32 v43, 0xbfb8aa3b, v43
	v_mul_f32_e32 v44, 0xbfb8aa3b, v44
	v_mul_f32_e32 v45, 0xbfb8aa3b, v45
	v_exp_f32_e32 v46, v46
	v_exp_f32_e32 v47, v47
	v_exp_f32_e32 v48, v48
	v_exp_f32_e32 v49, v49
	v_exp_f32_e32 v42, v42
	v_exp_f32_e32 v43, v43
	v_exp_f32_e32 v44, v44
	v_exp_f32_e32 v45, v45
	v_add_f32_e32 v46, 1.0, v46
	v_add_f32_e32 v47, 1.0, v47
	v_add_f32_e32 v48, 1.0, v48
	v_add_f32_e32 v49, 1.0, v49
	v_add_f32_e32 v42, 1.0, v42
	v_add_f32_e32 v43, 1.0, v43
	v_add_f32_e32 v44, 1.0, v44
	v_add_f32_e32 v45, 1.0, v45
	v_rcp_f32_e32 v46, v46
	v_rcp_f32_e32 v47, v47
	v_rcp_f32_e32 v48, v48
	v_rcp_f32_e32 v49, v49
	v_rcp_f32_e32 v42, v42
	v_rcp_f32_e32 v43, v43
	v_rcp_f32_e32 v44, v44
	v_rcp_f32_e32 v45, v45
	v_cvt_pk_bf16_f32 v156, v46, v47
	v_cvt_pk_bf16_f32 v157, v48, v49
	v_cvt_pk_bf16_f32 v158, v42, v43
	v_cvt_pk_bf16_f32 v159, v44, v45
	ds_bpermute_b32 v216, v226, v156
	ds_bpermute_b32 v217, v226, v157
	ds_bpermute_b32 v218, v226, v158
	ds_bpermute_b32 v219, v226, v159
	v_mul_f32_e32 v38, 0xbfb8aa3b, v38
	v_mul_f32_e32 v39, 0xbfb8aa3b, v39
	v_mul_f32_e32 v40, 0xbfb8aa3b, v40
	v_mul_f32_e32 v41, 0xbfb8aa3b, v41
	v_mul_f32_e32 v34, 0xbfb8aa3b, v34
	v_mul_f32_e32 v35, 0xbfb8aa3b, v35
	v_mul_f32_e32 v36, 0xbfb8aa3b, v36
	v_mul_f32_e32 v37, 0xbfb8aa3b, v37
	v_exp_f32_e32 v38, v38
	v_exp_f32_e32 v39, v39
	v_exp_f32_e32 v40, v40
	v_exp_f32_e32 v41, v41
	v_exp_f32_e32 v34, v34
	v_exp_f32_e32 v35, v35
	v_exp_f32_e32 v36, v36
	v_exp_f32_e32 v37, v37
	v_add_f32_e32 v38, 1.0, v38
	v_add_f32_e32 v39, 1.0, v39
	v_add_f32_e32 v40, 1.0, v40
	v_add_f32_e32 v41, 1.0, v41
	v_add_f32_e32 v34, 1.0, v34
	v_add_f32_e32 v35, 1.0, v35
	v_add_f32_e32 v36, 1.0, v36
	v_add_f32_e32 v37, 1.0, v37
	v_rcp_f32_e32 v38, v38
	v_rcp_f32_e32 v39, v39
	v_rcp_f32_e32 v40, v40
	v_rcp_f32_e32 v41, v41
	v_rcp_f32_e32 v34, v34
	v_rcp_f32_e32 v35, v35
	v_rcp_f32_e32 v36, v36
	v_rcp_f32_e32 v37, v37
	v_cvt_pk_bf16_f32 v160, v38, v39
	v_cvt_pk_bf16_f32 v161, v40, v41
	v_cvt_pk_bf16_f32 v162, v34, v35
	v_cvt_pk_bf16_f32 v163, v36, v37
	ds_bpermute_b32 v220, v226, v160
	ds_bpermute_b32 v221, v226, v161
	ds_bpermute_b32 v222, v226, v162
	ds_bpermute_b32 v223, v226, v163
	s_waitcnt lgkmcnt(0)
	global_store_dwordx4 v235, v[208:211], s[10:11] sc0 sc1
	global_store_dwordx4 v235, v[212:215], s[10:11] offset:256 sc0 sc1
	global_store_dwordx4 v235, v[216:219], s[20:21] sc0 sc1
	global_store_dwordx4 v235, v[220:223], s[20:21] offset:256 sc0 sc1
	s_add_u32 s10, s22, 0x1e0000
	s_addc_u32 s11, s23, 0
	v_mul_f32_e32 v28, 0xbfb8aa3b, v28
	v_mul_f32_e32 v29, 0xbfb8aa3b, v29
	v_mul_f32_e32 v30, 0xbfb8aa3b, v30
	v_mul_f32_e32 v31, 0xbfb8aa3b, v31
	v_mul_f32_e32 v24, 0xbfb8aa3b, v24
	v_mul_f32_e32 v25, 0xbfb8aa3b, v25
	v_mul_f32_e32 v26, 0xbfb8aa3b, v26
	v_mul_f32_e32 v27, 0xbfb8aa3b, v27
	v_exp_f32_e32 v28, v28
	v_exp_f32_e32 v29, v29
	v_exp_f32_e32 v30, v30
	v_exp_f32_e32 v31, v31
	v_exp_f32_e32 v24, v24
	v_exp_f32_e32 v25, v25
	v_exp_f32_e32 v26, v26
	v_exp_f32_e32 v27, v27
	v_add_f32_e32 v28, 1.0, v28
	v_add_f32_e32 v29, 1.0, v29
	v_add_f32_e32 v30, 1.0, v30
	v_add_f32_e32 v31, 1.0, v31
	v_add_f32_e32 v24, 1.0, v24
	v_add_f32_e32 v25, 1.0, v25
	v_add_f32_e32 v26, 1.0, v26
	v_add_f32_e32 v27, 1.0, v27
	v_rcp_f32_e32 v28, v28
	v_rcp_f32_e32 v29, v29
	v_rcp_f32_e32 v30, v30
	v_rcp_f32_e32 v31, v31
	v_rcp_f32_e32 v24, v24
	v_rcp_f32_e32 v25, v25
	v_rcp_f32_e32 v26, v26
	v_rcp_f32_e32 v27, v27
	v_cvt_pk_bf16_f32 v148, v28, v29
	v_cvt_pk_bf16_f32 v149, v30, v31
	v_cvt_pk_bf16_f32 v150, v24, v25
	v_cvt_pk_bf16_f32 v151, v26, v27
	ds_bpermute_b32 v238, v226, v148
	ds_bpermute_b32 v239, v226, v149
	ds_bpermute_b32 v240, v226, v150
	ds_bpermute_b32 v241, v226, v151
	v_mul_f32_e32 v20, 0xbfb8aa3b, v20
	v_mul_f32_e32 v21, 0xbfb8aa3b, v21
	v_mul_f32_e32 v22, 0xbfb8aa3b, v22
	v_mul_f32_e32 v23, 0xbfb8aa3b, v23
	v_mul_f32_e32 v16, 0xbfb8aa3b, v16
	v_mul_f32_e32 v17, 0xbfb8aa3b, v17
	v_mul_f32_e32 v18, 0xbfb8aa3b, v18
	v_mul_f32_e32 v19, 0xbfb8aa3b, v19
	v_exp_f32_e32 v20, v20
	v_exp_f32_e32 v21, v21
	v_exp_f32_e32 v22, v22
	v_exp_f32_e32 v23, v23
	v_exp_f32_e32 v16, v16
	v_exp_f32_e32 v17, v17
	v_exp_f32_e32 v18, v18
	v_exp_f32_e32 v19, v19
	v_add_f32_e32 v20, 1.0, v20
	v_add_f32_e32 v21, 1.0, v21
	v_add_f32_e32 v22, 1.0, v22
	v_add_f32_e32 v23, 1.0, v23
	v_add_f32_e32 v16, 1.0, v16
	v_add_f32_e32 v17, 1.0, v17
	v_add_f32_e32 v18, 1.0, v18
	v_add_f32_e32 v19, 1.0, v19
	v_rcp_f32_e32 v20, v20
	v_rcp_f32_e32 v21, v21
	v_rcp_f32_e32 v22, v22
	v_rcp_f32_e32 v23, v23
	v_rcp_f32_e32 v16, v16
	v_rcp_f32_e32 v17, v17
	v_rcp_f32_e32 v18, v18
	v_rcp_f32_e32 v19, v19
	v_cvt_pk_bf16_f32 v152, v20, v21
	v_cvt_pk_bf16_f32 v153, v22, v23
	v_cvt_pk_bf16_f32 v154, v16, v17
	v_cvt_pk_bf16_f32 v155, v18, v19
	ds_bpermute_b32 v242, v226, v152
	ds_bpermute_b32 v243, v226, v153
	ds_bpermute_b32 v244, v226, v154
	ds_bpermute_b32 v245, v226, v155
	s_add_u32 s20, s22, 0x210000
	s_addc_u32 s21, s23, 0
	v_mul_f32_e32 v12, 0xbfb8aa3b, v12
	v_mul_f32_e32 v13, 0xbfb8aa3b, v13
	v_mul_f32_e32 v14, 0xbfb8aa3b, v14
	v_mul_f32_e32 v15, 0xbfb8aa3b, v15
	v_mul_f32_e32 v8, 0xbfb8aa3b, v8
	v_mul_f32_e32 v9, 0xbfb8aa3b, v9
	v_mul_f32_e32 v10, 0xbfb8aa3b, v10
	v_mul_f32_e32 v11, 0xbfb8aa3b, v11
	v_exp_f32_e32 v12, v12
	v_exp_f32_e32 v13, v13
	v_exp_f32_e32 v14, v14
	v_exp_f32_e32 v15, v15
	v_exp_f32_e32 v8, v8
	v_exp_f32_e32 v9, v9
	v_exp_f32_e32 v10, v10
	v_exp_f32_e32 v11, v11
	v_add_f32_e32 v12, 1.0, v12
	v_add_f32_e32 v13, 1.0, v13
	v_add_f32_e32 v14, 1.0, v14
	v_add_f32_e32 v15, 1.0, v15
	v_add_f32_e32 v8, 1.0, v8
	v_add_f32_e32 v9, 1.0, v9
	v_add_f32_e32 v10, 1.0, v10
	v_add_f32_e32 v11, 1.0, v11
	v_rcp_f32_e32 v12, v12
	v_rcp_f32_e32 v13, v13
	v_rcp_f32_e32 v14, v14
	v_rcp_f32_e32 v15, v15
	v_rcp_f32_e32 v8, v8
	v_rcp_f32_e32 v9, v9
	v_rcp_f32_e32 v10, v10
	v_rcp_f32_e32 v11, v11
	v_cvt_pk_bf16_f32 v156, v12, v13
	v_cvt_pk_bf16_f32 v157, v14, v15
	v_cvt_pk_bf16_f32 v158, v8, v9
	v_cvt_pk_bf16_f32 v159, v10, v11
	ds_bpermute_b32 v246, v226, v156
	ds_bpermute_b32 v247, v226, v157
	ds_bpermute_b32 v248, v226, v158
	ds_bpermute_b32 v249, v226, v159
	v_mul_f32_e32 v4, 0xbfb8aa3b, v4
	v_mul_f32_e32 v5, 0xbfb8aa3b, v5
	v_mul_f32_e32 v6, 0xbfb8aa3b, v6
	v_mul_f32_e32 v7, 0xbfb8aa3b, v7
	v_mul_f32_e32 v0, 0xbfb8aa3b, v0
	v_mul_f32_e32 v1, 0xbfb8aa3b, v1
	v_mul_f32_e32 v2, 0xbfb8aa3b, v2
	v_mul_f32_e32 v3, 0xbfb8aa3b, v3
	v_exp_f32_e32 v4, v4
	v_exp_f32_e32 v5, v5
	v_exp_f32_e32 v6, v6
	v_exp_f32_e32 v7, v7
	v_exp_f32_e32 v0, v0
	v_exp_f32_e32 v1, v1
	v_exp_f32_e32 v2, v2
	v_exp_f32_e32 v3, v3
	v_add_f32_e32 v4, 1.0, v4
	v_add_f32_e32 v5, 1.0, v5
	v_add_f32_e32 v6, 1.0, v6
	v_add_f32_e32 v7, 1.0, v7
	v_add_f32_e32 v0, 1.0, v0
	v_add_f32_e32 v1, 1.0, v1
	v_add_f32_e32 v2, 1.0, v2
	v_add_f32_e32 v3, 1.0, v3
	v_rcp_f32_e32 v4, v4
	v_rcp_f32_e32 v5, v5
	v_rcp_f32_e32 v6, v6
	v_rcp_f32_e32 v7, v7
	v_rcp_f32_e32 v0, v0
	v_rcp_f32_e32 v1, v1
	v_rcp_f32_e32 v2, v2
	v_rcp_f32_e32 v3, v3
	v_cvt_pk_bf16_f32 v160, v4, v5
	v_cvt_pk_bf16_f32 v161, v6, v7
	v_cvt_pk_bf16_f32 v162, v0, v1
	v_cvt_pk_bf16_f32 v163, v2, v3
	ds_bpermute_b32 v250, v226, v160
	ds_bpermute_b32 v251, v226, v161
	ds_bpermute_b32 v252, v226, v162
	ds_bpermute_b32 v253, v226, v163
	s_waitcnt lgkmcnt(0)
	global_store_dwordx4 v235, v[238:241], s[10:11] sc0 sc1
	global_store_dwordx4 v235, v[242:245], s[10:11] offset:256 sc0 sc1
	global_store_dwordx4 v235, v[246:249], s[20:21] sc0 sc1
	global_store_dwordx4 v235, v[250:253], s[20:21] offset:256 sc0 sc1
	s_branch .Lmain_latch_fast
.Lmain_kv:
	s_bitcmp1_b32 s6, 1
	s_cbranch_scc0 .Lmain_old
	s_cmp_ge_u32 s6, 4
	s_cbranch_scc0 .Lmain_old
	s_mov_b32 s20, 0xcccccccc
	s_mov_b32 s21, 0xcccccccc
	s_mov_b32 s24, 0xf0f0f0f0
	s_mov_b32 s25, 0xf0f0f0f0
	s_mov_b32 s22, 0xaaaaaaaa
	s_mov_b32 s23, 0xaaaaaaaa
	v_mov_b32_e32 v227, 0x5040100
	v_mov_b32_e32 v152, 0x3020706
	v_cndmask_b32_e64 v227, v227, v152, s[22:23]
	v_and_b32_e32 v152, 1, v166
	v_and_b32_e32 v153, 4, v166
	v_lshrrev_b32_e32 v153, 1, v153
	v_and_b32_e32 v154, 2, v166
	v_lshlrev_b32_e32 v154, 1, v154
	v_or3_b32 v152, v152, v153, v154
	v_lshlrev_b32_e32 v228, 4, v152
	v_lshl_add_u32 v228, v32, 3, v228
	v_lshrrev_b32_e32 v153, 3, v166
	v_lshl_add_u32 v228, v153, 11, v228
	s_lshl_b32 s7, s45, 8
	v_add_u32_e32 v228, s7, v228
	s_lshr_b32 s7, s6, 1
	s_lshl_b32 s7, s7, 24
	s_add_u32 s22, s76, s7
	s_addc_u32 s23, s77, 0
	s_add_u32 s22, s22, 0x31e51000
	s_addc_u32 s23, s23, 0
	s_lshr_b32 s7, s31, 3
	s_lshl_b32 s7, s7, 2
	s_and_b32 s13, s6, 1
	s_lshl_b32 s13, s13, 1
	s_add_i32 s7, s7, s13
	s_lshl_b32 s7, s7, 19
	s_and_b32 s13, s31, 7
	s_lshl_b32 s13, s13, 16
	s_add_i32 s7, s7, s13
	s_add_u32 s22, s22, s7
	s_addc_u32 s23, s23, 0
	s_add_u32 s10, s22, 0
	s_addc_u32 s11, s23, 0
	v_cvt_pk_bf16_f32 v148, v126, v127
	v_cvt_pk_bf16_f32 v149, v128, v129
	v_cvt_pk_bf16_f32 v150, v122, v123
	v_cvt_pk_bf16_f32 v151, v124, v125
	s_nop 1
	v_mov_b32_dpp v152, v148 quad_perm:[1,0,3,2] row_mask:0xf bank_mask:0xf
	v_mov_b32_dpp v153, v149 quad_perm:[1,0,3,2] row_mask:0xf bank_mask:0xf
	v_mov_b32_dpp v154, v150 quad_perm:[1,0,3,2] row_mask:0xf bank_mask:0xf
	v_mov_b32_dpp v155, v151 quad_perm:[1,0,3,2] row_mask:0xf bank_mask:0xf
	v_perm_b32 v148, v152, v148, v227
	v_perm_b32 v149, v153, v149, v227
	v_perm_b32 v150, v154, v150, v227
	v_perm_b32 v151, v155, v151, v227
	v_cndmask_b32_e64 v160, v150, v148, s[20:21]
	v_cndmask_b32_e64 v161, v151, v149, s[20:21]
	s_nop 1
	v_mov_b32_dpp v162, v160 quad_perm:[2,3,0,1] row_mask:0xf bank_mask:0xf
	v_mov_b32_dpp v163, v161 quad_perm:[2,3,0,1] row_mask:0xf bank_mask:0xf
	v_cndmask_b32_e64 v156, v148, v162, s[20:21]
	v_cndmask_b32_e64 v157, v162, v150, s[20:21]
	v_cndmask_b32_e64 v158, v149, v163, s[20:21]
	v_cndmask_b32_e64 v159, v163, v151, s[20:21]
	v_cndmask_b32_e64 v160, v158, v156, s[24:25]
	v_cndmask_b32_e64 v161, v159, v157, s[24:25]
	s_nop 1
	v_mov_b32_dpp v162, v160 row_shl:4 row_mask:0xf bank_mask:0x5
	v_mov_b32_dpp v163, v161 row_shl:4 row_mask:0xf bank_mask:0x5
	v_mov_b32_dpp v162, v160 row_shr:4 row_mask:0xf bank_mask:0xa
	v_mov_b32_dpp v163, v161 row_shr:4 row_mask:0xf bank_mask:0xa
	v_cndmask_b32_e64 v172, v156, v162, s[24:25]
	v_cndmask_b32_e64 v173, v157, v163, s[24:25]
	v_cndmask_b32_e64 v174, v162, v158, s[24:25]
	v_cndmask_b32_e64 v175, v163, v159, s[24:25]
	global_store_dwordx4 v228, v[172:175], s[10:11]
	s_add_u32 s10, s22, 0x80000
	s_addc_u32 s11, s23, 0
	v_cvt_pk_bf16_f32 v148, v118, v119
	v_cvt_pk_bf16_f32 v149, v120, v121
	v_cvt_pk_bf16_f32 v150, v114, v115
	v_cvt_pk_bf16_f32 v151, v116, v117
	s_nop 1
	v_mov_b32_dpp v152, v148 quad_perm:[1,0,3,2] row_mask:0xf bank_mask:0xf
	v_mov_b32_dpp v153, v149 quad_perm:[1,0,3,2] row_mask:0xf bank_mask:0xf
	v_mov_b32_dpp v154, v150 quad_perm:[1,0,3,2] row_mask:0xf bank_mask:0xf
	v_mov_b32_dpp v155, v151 quad_perm:[1,0,3,2] row_mask:0xf bank_mask:0xf
	v_perm_b32 v148, v152, v148, v227
	v_perm_b32 v149, v153, v149, v227
	v_perm_b32 v150, v154, v150, v227
	v_perm_b32 v151, v155, v151, v227
	v_cndmask_b32_e64 v160, v150, v148, s[20:21]
	v_cndmask_b32_e64 v161, v151, v149, s[20:21]
	s_nop 1
	v_mov_b32_dpp v162, v160 quad_perm:[2,3,0,1] row_mask:0xf bank_mask:0xf
	v_mov_b32_dpp v163, v161 quad_perm:[2,3,0,1] row_mask:0xf bank_mask:0xf
	v_cndmask_b32_e64 v156, v148, v162, s[20:21]
	v_cndmask_b32_e64 v157, v162, v150, s[20:21]
	v_cndmask_b32_e64 v158, v149, v163, s[20:21]
	v_cndmask_b32_e64 v159, v163, v151, s[20:21]
	v_cndmask_b32_e64 v160, v158, v156, s[24:25]
	v_cndmask_b32_e64 v161, v159, v157, s[24:25]
	s_nop 1
	v_mov_b32_dpp v162, v160 row_shl:4 row_mask:0xf bank_mask:0x5
	v_mov_b32_dpp v163, v161 row_shl:4 row_mask:0xf bank_mask:0x5
	v_mov_b32_dpp v162, v160 row_shr:4 row_mask:0xf bank_mask:0xa
	v_mov_b32_dpp v163, v161 row_shr:4 row_mask:0xf bank_mask:0xa
	v_cndmask_b32_e64 v180, v156, v162, s[24:25]
	v_cndmask_b32_e64 v181, v157, v163, s[24:25]
	v_cndmask_b32_e64 v182, v162, v158, s[24:25]
	v_cndmask_b32_e64 v183, v163, v159, s[24:25]
	global_store_dwordx4 v228, v[180:183], s[10:11]
	s_add_u32 s10, s22, 0x1000
	s_addc_u32 s11, s23, 0
	v_cvt_pk_bf16_f32 v148, v110, v111
	v_cvt_pk_bf16_f32 v149, v112, v113
	v_cvt_pk_bf16_f32 v150, v106, v107
	v_cvt_pk_bf16_f32 v151, v108, v109
	s_nop 1
	v_mov_b32_dpp v152, v148 quad_perm:[1,0,3,2] row_mask:0xf bank_mask:0xf
	v_mov_b32_dpp v153, v149 quad_perm:[1,0,3,2] row_mask:0xf bank_mask:0xf
	v_mov_b32_dpp v154, v150 quad_perm:[1,0,3,2] row_mask:0xf bank_mask:0xf
	v_mov_b32_dpp v155, v151 quad_perm:[1,0,3,2] row_mask:0xf bank_mask:0xf
	v_perm_b32 v148, v152, v148, v227
	v_perm_b32 v149, v153, v149, v227
	v_perm_b32 v150, v154, v150, v227
	v_perm_b32 v151, v155, v151, v227
	v_cndmask_b32_e64 v160, v150, v148, s[20:21]
	v_cndmask_b32_e64 v161, v151, v149, s[20:21]
	s_nop 1
	v_mov_b32_dpp v162, v160 quad_perm:[2,3,0,1] row_mask:0xf bank_mask:0xf
	v_mov_b32_dpp v163, v161 quad_perm:[2,3,0,1] row_mask:0xf bank_mask:0xf
	v_cndmask_b32_e64 v156, v148, v162, s[20:21]
	v_cndmask_b32_e64 v157, v162, v150, s[20:21]
	v_cndmask_b32_e64 v158, v149, v163, s[20:21]
	v_cndmask_b32_e64 v159, v163, v151, s[20:21]
	v_cndmask_b32_e64 v160, v158, v156, s[24:25]
	v_cndmask_b32_e64 v161, v159, v157, s[24:25]
	s_nop 1
	v_mov_b32_dpp v162, v160 row_shl:4 row_mask:0xf bank_mask:0x5
	v_mov_b32_dpp v163, v161 row_shl:4 row_mask:0xf bank_mask:0x5
	v_mov_b32_dpp v162, v160 row_shr:4 row_mask:0xf bank_mask:0xa
	v_mov_b32_dpp v163, v161 row_shr:4 row_mask:0xf bank_mask:0xa
	v_cndmask_b32_e64 v184, v156, v162, s[24:25]
	v_cndmask_b32_e64 v185, v157, v163, s[24:25]
	v_cndmask_b32_e64 v186, v162, v158, s[24:25]
	v_cndmask_b32_e64 v187, v163, v159, s[24:25]
	global_store_dwordx4 v228, v[184:187], s[10:11]
	s_add_u32 s10, s22, 0x81000
	s_addc_u32 s11, s23, 0
	v_cvt_pk_bf16_f32 v148, v102, v103
	v_cvt_pk_bf16_f32 v149, v104, v105
	v_cvt_pk_bf16_f32 v150, v98, v99
	v_cvt_pk_bf16_f32 v151, v100, v101
	s_nop 1
	v_mov_b32_dpp v152, v148 quad_perm:[1,0,3,2] row_mask:0xf bank_mask:0xf
	v_mov_b32_dpp v153, v149 quad_perm:[1,0,3,2] row_mask:0xf bank_mask:0xf
	v_mov_b32_dpp v154, v150 quad_perm:[1,0,3,2] row_mask:0xf bank_mask:0xf
	v_mov_b32_dpp v155, v151 quad_perm:[1,0,3,2] row_mask:0xf bank_mask:0xf
	v_perm_b32 v148, v152, v148, v227
	v_perm_b32 v149, v153, v149, v227
	v_perm_b32 v150, v154, v150, v227
	v_perm_b32 v151, v155, v151, v227
	v_cndmask_b32_e64 v160, v150, v148, s[20:21]
	v_cndmask_b32_e64 v161, v151, v149, s[20:21]
	s_nop 1
	v_mov_b32_dpp v162, v160 quad_perm:[2,3,0,1] row_mask:0xf bank_mask:0xf
	v_mov_b32_dpp v163, v161 quad_perm:[2,3,0,1] row_mask:0xf bank_mask:0xf
	v_cndmask_b32_e64 v156, v148, v162, s[20:21]
	v_cndmask_b32_e64 v157, v162, v150, s[20:21]
	v_cndmask_b32_e64 v158, v149, v163, s[20:21]
	v_cndmask_b32_e64 v159, v163, v151, s[20:21]
	v_cndmask_b32_e64 v160, v158, v156, s[24:25]
	v_cndmask_b32_e64 v161, v159, v157, s[24:25]
	s_nop 1
	v_mov_b32_dpp v162, v160 row_shl:4 row_mask:0xf bank_mask:0x5
	v_mov_b32_dpp v163, v161 row_shl:4 row_mask:0xf bank_mask:0x5
	v_mov_b32_dpp v162, v160 row_shr:4 row_mask:0xf bank_mask:0xa
	v_mov_b32_dpp v163, v161 row_shr:4 row_mask:0xf bank_mask:0xa
	v_cndmask_b32_e64 v188, v156, v162, s[24:25]
	v_cndmask_b32_e64 v189, v157, v163, s[24:25]
	v_cndmask_b32_e64 v190, v162, v158, s[24:25]
	v_cndmask_b32_e64 v191, v163, v159, s[24:25]
	global_store_dwordx4 v228, v[188:191], s[10:11]
	s_add_u32 s10, s22, 0x2000
	s_addc_u32 s11, s23, 0
	v_cvt_pk_bf16_f32 v148, v94, v95
	v_cvt_pk_bf16_f32 v149, v96, v97
	v_cvt_pk_bf16_f32 v150, v90, v91
	v_cvt_pk_bf16_f32 v151, v92, v93
	s_nop 1
	v_mov_b32_dpp v152, v148 quad_perm:[1,0,3,2] row_mask:0xf bank_mask:0xf
	v_mov_b32_dpp v153, v149 quad_perm:[1,0,3,2] row_mask:0xf bank_mask:0xf
	v_mov_b32_dpp v154, v150 quad_perm:[1,0,3,2] row_mask:0xf bank_mask:0xf
	v_mov_b32_dpp v155, v151 quad_perm:[1,0,3,2] row_mask:0xf bank_mask:0xf
	v_perm_b32 v148, v152, v148, v227
	v_perm_b32 v149, v153, v149, v227
	v_perm_b32 v150, v154, v150, v227
	v_perm_b32 v151, v155, v151, v227
	v_cndmask_b32_e64 v160, v150, v148, s[20:21]
	v_cndmask_b32_e64 v161, v151, v149, s[20:21]
	s_nop 1
	v_mov_b32_dpp v162, v160 quad_perm:[2,3,0,1] row_mask:0xf bank_mask:0xf
	v_mov_b32_dpp v163, v161 quad_perm:[2,3,0,1] row_mask:0xf bank_mask:0xf
	v_cndmask_b32_e64 v156, v148, v162, s[20:21]
	v_cndmask_b32_e64 v157, v162, v150, s[20:21]
	v_cndmask_b32_e64 v158, v149, v163, s[20:21]
	v_cndmask_b32_e64 v159, v163, v151, s[20:21]
	v_cndmask_b32_e64 v160, v158, v156, s[24:25]
	v_cndmask_b32_e64 v161, v159, v157, s[24:25]
	s_nop 1
	v_mov_b32_dpp v162, v160 row_shl:4 row_mask:0xf bank_mask:0x5
	v_mov_b32_dpp v163, v161 row_shl:4 row_mask:0xf bank_mask:0x5
	v_mov_b32_dpp v162, v160 row_shr:4 row_mask:0xf bank_mask:0xa
	v_mov_b32_dpp v163, v161 row_shr:4 row_mask:0xf bank_mask:0xa
	v_cndmask_b32_e64 v192, v156, v162, s[24:25]
	v_cndmask_b32_e64 v193, v157, v163, s[24:25]
	v_cndmask_b32_e64 v194, v162, v158, s[24:25]
	v_cndmask_b32_e64 v195, v163, v159, s[24:25]
	global_store_dwordx4 v228, v[192:195], s[10:11]
	s_add_u32 s10, s22, 0x82000
	s_addc_u32 s11, s23, 0
	v_cvt_pk_bf16_f32 v148, v86, v87
	v_cvt_pk_bf16_f32 v149, v88, v89
	v_cvt_pk_bf16_f32 v150, v82, v83
	v_cvt_pk_bf16_f32 v151, v84, v85
	s_nop 1
	v_mov_b32_dpp v152, v148 quad_perm:[1,0,3,2] row_mask:0xf bank_mask:0xf
	v_mov_b32_dpp v153, v149 quad_perm:[1,0,3,2] row_mask:0xf bank_mask:0xf
	v_mov_b32_dpp v154, v150 quad_perm:[1,0,3,2] row_mask:0xf bank_mask:0xf
	v_mov_b32_dpp v155, v151 quad_perm:[1,0,3,2] row_mask:0xf bank_mask:0xf
	v_perm_b32 v148, v152, v148, v227
	v_perm_b32 v149, v153, v149, v227
	v_perm_b32 v150, v154, v150, v227
	v_perm_b32 v151, v155, v151, v227
	v_cndmask_b32_e64 v160, v150, v148, s[20:21]
	v_cndmask_b32_e64 v161, v151, v149, s[20:21]
	s_nop 1
	v_mov_b32_dpp v162, v160 quad_perm:[2,3,0,1] row_mask:0xf bank_mask:0xf
	v_mov_b32_dpp v163, v161 quad_perm:[2,3,0,1] row_mask:0xf bank_mask:0xf
	v_cndmask_b32_e64 v156, v148, v162, s[20:21]
	v_cndmask_b32_e64 v157, v162, v150, s[20:21]
	v_cndmask_b32_e64 v158, v149, v163, s[20:21]
	v_cndmask_b32_e64 v159, v163, v151, s[20:21]
	v_cndmask_b32_e64 v160, v158, v156, s[24:25]
	v_cndmask_b32_e64 v161, v159, v157, s[24:25]
	s_nop 1
	v_mov_b32_dpp v162, v160 row_shl:4 row_mask:0xf bank_mask:0x5
	v_mov_b32_dpp v163, v161 row_shl:4 row_mask:0xf bank_mask:0x5
	v_mov_b32_dpp v162, v160 row_shr:4 row_mask:0xf bank_mask:0xa
	v_mov_b32_dpp v163, v161 row_shr:4 row_mask:0xf bank_mask:0xa
	v_cndmask_b32_e64 v196, v156, v162, s[24:25]
	v_cndmask_b32_e64 v197, v157, v163, s[24:25]
	v_cndmask_b32_e64 v198, v162, v158, s[24:25]
	v_cndmask_b32_e64 v199, v163, v159, s[24:25]
	global_store_dwordx4 v228, v[196:199], s[10:11]
	s_add_u32 s10, s22, 0x3000
	s_addc_u32 s11, s23, 0
	v_cvt_pk_bf16_f32 v148, v78, v79
	v_cvt_pk_bf16_f32 v149, v80, v81
	v_cvt_pk_bf16_f32 v150, v74, v75
	v_cvt_pk_bf16_f32 v151, v76, v77
	s_nop 1
	v_mov_b32_dpp v152, v148 quad_perm:[1,0,3,2] row_mask:0xf bank_mask:0xf
	v_mov_b32_dpp v153, v149 quad_perm:[1,0,3,2] row_mask:0xf bank_mask:0xf
	v_mov_b32_dpp v154, v150 quad_perm:[1,0,3,2] row_mask:0xf bank_mask:0xf
	v_mov_b32_dpp v155, v151 quad_perm:[1,0,3,2] row_mask:0xf bank_mask:0xf
	v_perm_b32 v148, v152, v148, v227
	v_perm_b32 v149, v153, v149, v227
	v_perm_b32 v150, v154, v150, v227
	v_perm_b32 v151, v155, v151, v227
	v_cndmask_b32_e64 v160, v150, v148, s[20:21]
	v_cndmask_b32_e64 v161, v151, v149, s[20:21]
	s_nop 1
	v_mov_b32_dpp v162, v160 quad_perm:[2,3,0,1] row_mask:0xf bank_mask:0xf
	v_mov_b32_dpp v163, v161 quad_perm:[2,3,0,1] row_mask:0xf bank_mask:0xf
	v_cndmask_b32_e64 v156, v148, v162, s[20:21]
	v_cndmask_b32_e64 v157, v162, v150, s[20:21]
	v_cndmask_b32_e64 v158, v149, v163, s[20:21]
	v_cndmask_b32_e64 v159, v163, v151, s[20:21]
	v_cndmask_b32_e64 v160, v158, v156, s[24:25]
	v_cndmask_b32_e64 v161, v159, v157, s[24:25]
	s_nop 1
	v_mov_b32_dpp v162, v160 row_shl:4 row_mask:0xf bank_mask:0x5
	v_mov_b32_dpp v163, v161 row_shl:4 row_mask:0xf bank_mask:0x5
	v_mov_b32_dpp v162, v160 row_shr:4 row_mask:0xf bank_mask:0xa
	v_mov_b32_dpp v163, v161 row_shr:4 row_mask:0xf bank_mask:0xa
	v_cndmask_b32_e64 v200, v156, v162, s[24:25]
	v_cndmask_b32_e64 v201, v157, v163, s[24:25]
	v_cndmask_b32_e64 v202, v162, v158, s[24:25]
	v_cndmask_b32_e64 v203, v163, v159, s[24:25]
	global_store_dwordx4 v228, v[200:203], s[10:11]
	s_add_u32 s10, s22, 0x83000
	s_addc_u32 s11, s23, 0
	v_cvt_pk_bf16_f32 v148, v70, v71
	v_cvt_pk_bf16_f32 v149, v72, v73
	v_cvt_pk_bf16_f32 v150, v66, v67
	v_cvt_pk_bf16_f32 v151, v68, v69
	s_nop 1
	v_mov_b32_dpp v152, v148 quad_perm:[1,0,3,2] row_mask:0xf bank_mask:0xf
	v_mov_b32_dpp v153, v149 quad_perm:[1,0,3,2] row_mask:0xf bank_mask:0xf
	v_mov_b32_dpp v154, v150 quad_perm:[1,0,3,2] row_mask:0xf bank_mask:0xf
	v_mov_b32_dpp v155, v151 quad_perm:[1,0,3,2] row_mask:0xf bank_mask:0xf
	v_perm_b32 v148, v152, v148, v227
	v_perm_b32 v149, v153, v149, v227
	v_perm_b32 v150, v154, v150, v227
	v_perm_b32 v151, v155, v151, v227
	v_cndmask_b32_e64 v160, v150, v148, s[20:21]
	v_cndmask_b32_e64 v161, v151, v149, s[20:21]
	s_nop 1
	v_mov_b32_dpp v162, v160 quad_perm:[2,3,0,1] row_mask:0xf bank_mask:0xf
	v_mov_b32_dpp v163, v161 quad_perm:[2,3,0,1] row_mask:0xf bank_mask:0xf
	v_cndmask_b32_e64 v156, v148, v162, s[20:21]
	v_cndmask_b32_e64 v157, v162, v150, s[20:21]
	v_cndmask_b32_e64 v158, v149, v163, s[20:21]
	v_cndmask_b32_e64 v159, v163, v151, s[20:21]
	v_cndmask_b32_e64 v160, v158, v156, s[24:25]
	v_cndmask_b32_e64 v161, v159, v157, s[24:25]
	s_nop 1
	v_mov_b32_dpp v162, v160 row_shl:4 row_mask:0xf bank_mask:0x5
	v_mov_b32_dpp v163, v161 row_shl:4 row_mask:0xf bank_mask:0x5
	v_mov_b32_dpp v162, v160 row_shr:4 row_mask:0xf bank_mask:0xa
	v_mov_b32_dpp v163, v161 row_shr:4 row_mask:0xf bank_mask:0xa
	v_cndmask_b32_e64 v204, v156, v162, s[24:25]
	v_cndmask_b32_e64 v205, v157, v163, s[24:25]
	v_cndmask_b32_e64 v206, v162, v158, s[24:25]
	v_cndmask_b32_e64 v207, v163, v159, s[24:25]
	global_store_dwordx4 v228, v[204:207], s[10:11]
	s_add_u32 s10, s22, 0x8000
	s_addc_u32 s11, s23, 0
	v_cvt_pk_bf16_f32 v148, v62, v63
	v_cvt_pk_bf16_f32 v149, v64, v65
	v_cvt_pk_bf16_f32 v150, v58, v59
	v_cvt_pk_bf16_f32 v151, v60, v61
	s_nop 1
	v_mov_b32_dpp v152, v148 quad_perm:[1,0,3,2] row_mask:0xf bank_mask:0xf
	v_mov_b32_dpp v153, v149 quad_perm:[1,0,3,2] row_mask:0xf bank_mask:0xf
	v_mov_b32_dpp v154, v150 quad_perm:[1,0,3,2] row_mask:0xf bank_mask:0xf
	v_mov_b32_dpp v155, v151 quad_perm:[1,0,3,2] row_mask:0xf bank_mask:0xf
	v_perm_b32 v148, v152, v148, v227
	v_perm_b32 v149, v153, v149, v227
	v_perm_b32 v150, v154, v150, v227
	v_perm_b32 v151, v155, v151, v227
	v_cndmask_b32_e64 v160, v150, v148, s[20:21]
	v_cndmask_b32_e64 v161, v151, v149, s[20:21]
	s_nop 1
	v_mov_b32_dpp v162, v160 quad_perm:[2,3,0,1] row_mask:0xf bank_mask:0xf
	v_mov_b32_dpp v163, v161 quad_perm:[2,3,0,1] row_mask:0xf bank_mask:0xf
	v_cndmask_b32_e64 v156, v148, v162, s[20:21]
	v_cndmask_b32_e64 v157, v162, v150, s[20:21]
	v_cndmask_b32_e64 v158, v149, v163, s[20:21]
	v_cndmask_b32_e64 v159, v163, v151, s[20:21]
	v_cndmask_b32_e64 v160, v158, v156, s[24:25]
	v_cndmask_b32_e64 v161, v159, v157, s[24:25]
	s_nop 1
	v_mov_b32_dpp v162, v160 row_shl:4 row_mask:0xf bank_mask:0x5
	v_mov_b32_dpp v163, v161 row_shl:4 row_mask:0xf bank_mask:0x5
	v_mov_b32_dpp v162, v160 row_shr:4 row_mask:0xf bank_mask:0xa
	v_mov_b32_dpp v163, v161 row_shr:4 row_mask:0xf bank_mask:0xa
	v_cndmask_b32_e64 v208, v156, v162, s[24:25]
	v_cndmask_b32_e64 v209, v157, v163, s[24:25]
	v_cndmask_b32_e64 v210, v162, v158, s[24:25]
	v_cndmask_b32_e64 v211, v163, v159, s[24:25]
	global_store_dwordx4 v228, v[208:211], s[10:11]
	s_add_u32 s10, s22, 0x88000
	s_addc_u32 s11, s23, 0
	v_cvt_pk_bf16_f32 v148, v54, v55
	v_cvt_pk_bf16_f32 v149, v56, v57
	v_cvt_pk_bf16_f32 v150, v50, v51
	v_cvt_pk_bf16_f32 v151, v52, v53
	s_nop 1
	v_mov_b32_dpp v152, v148 quad_perm:[1,0,3,2] row_mask:0xf bank_mask:0xf
	v_mov_b32_dpp v153, v149 quad_perm:[1,0,3,2] row_mask:0xf bank_mask:0xf
	v_mov_b32_dpp v154, v150 quad_perm:[1,0,3,2] row_mask:0xf bank_mask:0xf
	v_mov_b32_dpp v155, v151 quad_perm:[1,0,3,2] row_mask:0xf bank_mask:0xf
	v_perm_b32 v148, v152, v148, v227
	v_perm_b32 v149, v153, v149, v227
	v_perm_b32 v150, v154, v150, v227
	v_perm_b32 v151, v155, v151, v227
	v_cndmask_b32_e64 v160, v150, v148, s[20:21]
	v_cndmask_b32_e64 v161, v151, v149, s[20:21]
	s_nop 1
	v_mov_b32_dpp v162, v160 quad_perm:[2,3,0,1] row_mask:0xf bank_mask:0xf
	v_mov_b32_dpp v163, v161 quad_perm:[2,3,0,1] row_mask:0xf bank_mask:0xf
	v_cndmask_b32_e64 v156, v148, v162, s[20:21]
	v_cndmask_b32_e64 v157, v162, v150, s[20:21]
	v_cndmask_b32_e64 v158, v149, v163, s[20:21]
	v_cndmask_b32_e64 v159, v163, v151, s[20:21]
	v_cndmask_b32_e64 v160, v158, v156, s[24:25]
	v_cndmask_b32_e64 v161, v159, v157, s[24:25]
	s_nop 1
	v_mov_b32_dpp v162, v160 row_shl:4 row_mask:0xf bank_mask:0x5
	v_mov_b32_dpp v163, v161 row_shl:4 row_mask:0xf bank_mask:0x5
	v_mov_b32_dpp v162, v160 row_shr:4 row_mask:0xf bank_mask:0xa
	v_mov_b32_dpp v163, v161 row_shr:4 row_mask:0xf bank_mask:0xa
	v_cndmask_b32_e64 v212, v156, v162, s[24:25]
	v_cndmask_b32_e64 v213, v157, v163, s[24:25]
	v_cndmask_b32_e64 v214, v162, v158, s[24:25]
	v_cndmask_b32_e64 v215, v163, v159, s[24:25]
	global_store_dwordx4 v228, v[212:215], s[10:11]
	s_add_u32 s10, s22, 0x9000
	s_addc_u32 s11, s23, 0
	v_cvt_pk_bf16_f32 v148, v46, v47
	v_cvt_pk_bf16_f32 v149, v48, v49
	v_cvt_pk_bf16_f32 v150, v42, v43
	v_cvt_pk_bf16_f32 v151, v44, v45
	s_nop 1
	v_mov_b32_dpp v152, v148 quad_perm:[1,0,3,2] row_mask:0xf bank_mask:0xf
	v_mov_b32_dpp v153, v149 quad_perm:[1,0,3,2] row_mask:0xf bank_mask:0xf
	v_mov_b32_dpp v154, v150 quad_perm:[1,0,3,2] row_mask:0xf bank_mask:0xf
	v_mov_b32_dpp v155, v151 quad_perm:[1,0,3,2] row_mask:0xf bank_mask:0xf
	v_perm_b32 v148, v152, v148, v227
	v_perm_b32 v149, v153, v149, v227
	v_perm_b32 v150, v154, v150, v227
	v_perm_b32 v151, v155, v151, v227
	v_cndmask_b32_e64 v160, v150, v148, s[20:21]
	v_cndmask_b32_e64 v161, v151, v149, s[20:21]
	s_nop 1
	v_mov_b32_dpp v162, v160 quad_perm:[2,3,0,1] row_mask:0xf bank_mask:0xf
	v_mov_b32_dpp v163, v161 quad_perm:[2,3,0,1] row_mask:0xf bank_mask:0xf
	v_cndmask_b32_e64 v156, v148, v162, s[20:21]
	v_cndmask_b32_e64 v157, v162, v150, s[20:21]
	v_cndmask_b32_e64 v158, v149, v163, s[20:21]
	v_cndmask_b32_e64 v159, v163, v151, s[20:21]
	v_cndmask_b32_e64 v160, v158, v156, s[24:25]
	v_cndmask_b32_e64 v161, v159, v157, s[24:25]
	s_nop 1
	v_mov_b32_dpp v162, v160 row_shl:4 row_mask:0xf bank_mask:0x5
	v_mov_b32_dpp v163, v161 row_shl:4 row_mask:0xf bank_mask:0x5
	v_mov_b32_dpp v162, v160 row_shr:4 row_mask:0xf bank_mask:0xa
	v_mov_b32_dpp v163, v161 row_shr:4 row_mask:0xf bank_mask:0xa
	v_cndmask_b32_e64 v216, v156, v162, s[24:25]
	v_cndmask_b32_e64 v217, v157, v163, s[24:25]
	v_cndmask_b32_e64 v218, v162, v158, s[24:25]
	v_cndmask_b32_e64 v219, v163, v159, s[24:25]
	global_store_dwordx4 v228, v[216:219], s[10:11]
	s_add_u32 s10, s22, 0x89000
	s_addc_u32 s11, s23, 0
	v_cvt_pk_bf16_f32 v148, v38, v39
	v_cvt_pk_bf16_f32 v149, v40, v41
	v_cvt_pk_bf16_f32 v150, v34, v35
	v_cvt_pk_bf16_f32 v151, v36, v37
	s_nop 1
	v_mov_b32_dpp v152, v148 quad_perm:[1,0,3,2] row_mask:0xf bank_mask:0xf
	v_mov_b32_dpp v153, v149 quad_perm:[1,0,3,2] row_mask:0xf bank_mask:0xf
	v_mov_b32_dpp v154, v150 quad_perm:[1,0,3,2] row_mask:0xf bank_mask:0xf
	v_mov_b32_dpp v155, v151 quad_perm:[1,0,3,2] row_mask:0xf bank_mask:0xf
	v_perm_b32 v148, v152, v148, v227
	v_perm_b32 v149, v153, v149, v227
	v_perm_b32 v150, v154, v150, v227
	v_perm_b32 v151, v155, v151, v227
	v_cndmask_b32_e64 v160, v150, v148, s[20:21]
	v_cndmask_b32_e64 v161, v151, v149, s[20:21]
	s_nop 1
	v_mov_b32_dpp v162, v160 quad_perm:[2,3,0,1] row_mask:0xf bank_mask:0xf
	v_mov_b32_dpp v163, v161 quad_perm:[2,3,0,1] row_mask:0xf bank_mask:0xf
	v_cndmask_b32_e64 v156, v148, v162, s[20:21]
	v_cndmask_b32_e64 v157, v162, v150, s[20:21]
	v_cndmask_b32_e64 v158, v149, v163, s[20:21]
	v_cndmask_b32_e64 v159, v163, v151, s[20:21]
	v_cndmask_b32_e64 v160, v158, v156, s[24:25]
	v_cndmask_b32_e64 v161, v159, v157, s[24:25]
	s_nop 1
	v_mov_b32_dpp v162, v160 row_shl:4 row_mask:0xf bank_mask:0x5
	v_mov_b32_dpp v163, v161 row_shl:4 row_mask:0xf bank_mask:0x5
	v_mov_b32_dpp v162, v160 row_shr:4 row_mask:0xf bank_mask:0xa
	v_mov_b32_dpp v163, v161 row_shr:4 row_mask:0xf bank_mask:0xa
	v_cndmask_b32_e64 v220, v156, v162, s[24:25]
	v_cndmask_b32_e64 v221, v157, v163, s[24:25]
	v_cndmask_b32_e64 v222, v162, v158, s[24:25]
	v_cndmask_b32_e64 v223, v163, v159, s[24:25]
	global_store_dwordx4 v228, v[220:223], s[10:11]
	s_add_u32 s10, s22, 0xa000
	s_addc_u32 s11, s23, 0
	v_cvt_pk_bf16_f32 v148, v28, v29
	v_cvt_pk_bf16_f32 v149, v30, v31
	v_cvt_pk_bf16_f32 v150, v24, v25
	v_cvt_pk_bf16_f32 v151, v26, v27
	s_nop 1
	v_mov_b32_dpp v152, v148 quad_perm:[1,0,3,2] row_mask:0xf bank_mask:0xf
	v_mov_b32_dpp v153, v149 quad_perm:[1,0,3,2] row_mask:0xf bank_mask:0xf
	v_mov_b32_dpp v154, v150 quad_perm:[1,0,3,2] row_mask:0xf bank_mask:0xf
	v_mov_b32_dpp v155, v151 quad_perm:[1,0,3,2] row_mask:0xf bank_mask:0xf
	v_perm_b32 v148, v152, v148, v227
	v_perm_b32 v149, v153, v149, v227
	v_perm_b32 v150, v154, v150, v227
	v_perm_b32 v151, v155, v151, v227
	v_cndmask_b32_e64 v160, v150, v148, s[20:21]
	v_cndmask_b32_e64 v161, v151, v149, s[20:21]
	s_nop 1
	v_mov_b32_dpp v162, v160 quad_perm:[2,3,0,1] row_mask:0xf bank_mask:0xf
	v_mov_b32_dpp v163, v161 quad_perm:[2,3,0,1] row_mask:0xf bank_mask:0xf
	v_cndmask_b32_e64 v156, v148, v162, s[20:21]
	v_cndmask_b32_e64 v157, v162, v150, s[20:21]
	v_cndmask_b32_e64 v158, v149, v163, s[20:21]
	v_cndmask_b32_e64 v159, v163, v151, s[20:21]
	v_cndmask_b32_e64 v160, v158, v156, s[24:25]
	v_cndmask_b32_e64 v161, v159, v157, s[24:25]
	s_nop 1
	v_mov_b32_dpp v162, v160 row_shl:4 row_mask:0xf bank_mask:0x5
	v_mov_b32_dpp v163, v161 row_shl:4 row_mask:0xf bank_mask:0x5
	v_mov_b32_dpp v162, v160 row_shr:4 row_mask:0xf bank_mask:0xa
	v_mov_b32_dpp v163, v161 row_shr:4 row_mask:0xf bank_mask:0xa
	v_cndmask_b32_e64 v238, v156, v162, s[24:25]
	v_cndmask_b32_e64 v239, v157, v163, s[24:25]
	v_cndmask_b32_e64 v240, v162, v158, s[24:25]
	v_cndmask_b32_e64 v241, v163, v159, s[24:25]
	global_store_dwordx4 v228, v[238:241], s[10:11]
	s_add_u32 s10, s22, 0x8a000
	s_addc_u32 s11, s23, 0
	v_cvt_pk_bf16_f32 v148, v20, v21
	v_cvt_pk_bf16_f32 v149, v22, v23
	v_cvt_pk_bf16_f32 v150, v16, v17
	v_cvt_pk_bf16_f32 v151, v18, v19
	s_nop 1
	v_mov_b32_dpp v152, v148 quad_perm:[1,0,3,2] row_mask:0xf bank_mask:0xf
	v_mov_b32_dpp v153, v149 quad_perm:[1,0,3,2] row_mask:0xf bank_mask:0xf
	v_mov_b32_dpp v154, v150 quad_perm:[1,0,3,2] row_mask:0xf bank_mask:0xf
	v_mov_b32_dpp v155, v151 quad_perm:[1,0,3,2] row_mask:0xf bank_mask:0xf
	v_perm_b32 v148, v152, v148, v227
	v_perm_b32 v149, v153, v149, v227
	v_perm_b32 v150, v154, v150, v227
	v_perm_b32 v151, v155, v151, v227
	v_cndmask_b32_e64 v160, v150, v148, s[20:21]
	v_cndmask_b32_e64 v161, v151, v149, s[20:21]
	s_nop 1
	v_mov_b32_dpp v162, v160 quad_perm:[2,3,0,1] row_mask:0xf bank_mask:0xf
	v_mov_b32_dpp v163, v161 quad_perm:[2,3,0,1] row_mask:0xf bank_mask:0xf
	v_cndmask_b32_e64 v156, v148, v162, s[20:21]
	v_cndmask_b32_e64 v157, v162, v150, s[20:21]
	v_cndmask_b32_e64 v158, v149, v163, s[20:21]
	v_cndmask_b32_e64 v159, v163, v151, s[20:21]
	v_cndmask_b32_e64 v160, v158, v156, s[24:25]
	v_cndmask_b32_e64 v161, v159, v157, s[24:25]
	s_nop 1
	v_mov_b32_dpp v162, v160 row_shl:4 row_mask:0xf bank_mask:0x5
	v_mov_b32_dpp v163, v161 row_shl:4 row_mask:0xf bank_mask:0x5
	v_mov_b32_dpp v162, v160 row_shr:4 row_mask:0xf bank_mask:0xa
	v_mov_b32_dpp v163, v161 row_shr:4 row_mask:0xf bank_mask:0xa
	v_cndmask_b32_e64 v242, v156, v162, s[24:25]
	v_cndmask_b32_e64 v243, v157, v163, s[24:25]
	v_cndmask_b32_e64 v244, v162, v158, s[24:25]
	v_cndmask_b32_e64 v245, v163, v159, s[24:25]
	global_store_dwordx4 v228, v[242:245], s[10:11]
	s_add_u32 s10, s22, 0xb000
	s_addc_u32 s11, s23, 0
	v_cvt_pk_bf16_f32 v148, v12, v13
	v_cvt_pk_bf16_f32 v149, v14, v15
	v_cvt_pk_bf16_f32 v150, v8, v9
	v_cvt_pk_bf16_f32 v151, v10, v11
	s_nop 1
	v_mov_b32_dpp v152, v148 quad_perm:[1,0,3,2] row_mask:0xf bank_mask:0xf
	v_mov_b32_dpp v153, v149 quad_perm:[1,0,3,2] row_mask:0xf bank_mask:0xf
	v_mov_b32_dpp v154, v150 quad_perm:[1,0,3,2] row_mask:0xf bank_mask:0xf
	v_mov_b32_dpp v155, v151 quad_perm:[1,0,3,2] row_mask:0xf bank_mask:0xf
	v_perm_b32 v148, v152, v148, v227
	v_perm_b32 v149, v153, v149, v227
	v_perm_b32 v150, v154, v150, v227
	v_perm_b32 v151, v155, v151, v227
	v_cndmask_b32_e64 v160, v150, v148, s[20:21]
	v_cndmask_b32_e64 v161, v151, v149, s[20:21]
	s_nop 1
	v_mov_b32_dpp v162, v160 quad_perm:[2,3,0,1] row_mask:0xf bank_mask:0xf
	v_mov_b32_dpp v163, v161 quad_perm:[2,3,0,1] row_mask:0xf bank_mask:0xf
	v_cndmask_b32_e64 v156, v148, v162, s[20:21]
	v_cndmask_b32_e64 v157, v162, v150, s[20:21]
	v_cndmask_b32_e64 v158, v149, v163, s[20:21]
	v_cndmask_b32_e64 v159, v163, v151, s[20:21]
	v_cndmask_b32_e64 v160, v158, v156, s[24:25]
	v_cndmask_b32_e64 v161, v159, v157, s[24:25]
	s_nop 1
	v_mov_b32_dpp v162, v160 row_shl:4 row_mask:0xf bank_mask:0x5
	v_mov_b32_dpp v163, v161 row_shl:4 row_mask:0xf bank_mask:0x5
	v_mov_b32_dpp v162, v160 row_shr:4 row_mask:0xf bank_mask:0xa
	v_mov_b32_dpp v163, v161 row_shr:4 row_mask:0xf bank_mask:0xa
	v_cndmask_b32_e64 v246, v156, v162, s[24:25]
	v_cndmask_b32_e64 v247, v157, v163, s[24:25]
	v_cndmask_b32_e64 v248, v162, v158, s[24:25]
	v_cndmask_b32_e64 v249, v163, v159, s[24:25]
	global_store_dwordx4 v228, v[246:249], s[10:11]
	s_add_u32 s10, s22, 0x8b000
	s_addc_u32 s11, s23, 0
	v_cvt_pk_bf16_f32 v148, v4, v5
	v_cvt_pk_bf16_f32 v149, v6, v7
	v_cvt_pk_bf16_f32 v150, v0, v1
	v_cvt_pk_bf16_f32 v151, v2, v3
	s_nop 1
	v_mov_b32_dpp v152, v148 quad_perm:[1,0,3,2] row_mask:0xf bank_mask:0xf
	v_mov_b32_dpp v153, v149 quad_perm:[1,0,3,2] row_mask:0xf bank_mask:0xf
	v_mov_b32_dpp v154, v150 quad_perm:[1,0,3,2] row_mask:0xf bank_mask:0xf
	v_mov_b32_dpp v155, v151 quad_perm:[1,0,3,2] row_mask:0xf bank_mask:0xf
	v_perm_b32 v148, v152, v148, v227
	v_perm_b32 v149, v153, v149, v227
	v_perm_b32 v150, v154, v150, v227
	v_perm_b32 v151, v155, v151, v227
	v_cndmask_b32_e64 v160, v150, v148, s[20:21]
	v_cndmask_b32_e64 v161, v151, v149, s[20:21]
	s_nop 1
	v_mov_b32_dpp v162, v160 quad_perm:[2,3,0,1] row_mask:0xf bank_mask:0xf
	v_mov_b32_dpp v163, v161 quad_perm:[2,3,0,1] row_mask:0xf bank_mask:0xf
	v_cndmask_b32_e64 v156, v148, v162, s[20:21]
	v_cndmask_b32_e64 v157, v162, v150, s[20:21]
	v_cndmask_b32_e64 v158, v149, v163, s[20:21]
	v_cndmask_b32_e64 v159, v163, v151, s[20:21]
	v_cndmask_b32_e64 v160, v158, v156, s[24:25]
	v_cndmask_b32_e64 v161, v159, v157, s[24:25]
	s_nop 1
	v_mov_b32_dpp v162, v160 row_shl:4 row_mask:0xf bank_mask:0x5
	v_mov_b32_dpp v163, v161 row_shl:4 row_mask:0xf bank_mask:0x5
	v_mov_b32_dpp v162, v160 row_shr:4 row_mask:0xf bank_mask:0xa
	v_mov_b32_dpp v163, v161 row_shr:4 row_mask:0xf bank_mask:0xa
	v_cndmask_b32_e64 v250, v156, v162, s[24:25]
	v_cndmask_b32_e64 v251, v157, v163, s[24:25]
	v_cndmask_b32_e64 v252, v162, v158, s[24:25]
	v_cndmask_b32_e64 v253, v163, v159, s[24:25]
	global_store_dwordx4 v228, v[250:253], s[10:11]
	s_branch .Lmain_latch_fast

.LBB0_1202:
	s_add_u32 s2, s6, 0x80080
	s_addc_u32 s3, s7, 0
	s_add_u32 s9, s4, 0x100
	s_addc_u32 s13, s5, 0
	s_mov_b32 s15, -2
	s_cmp_lg_u32 s22, 0
	s_cbranch_scc1 .Lbr_nozero
	v_mov_b32_e32 v0, 0
	v_mov_b32_e32 v1, v0
	v_mov_b32_e32 v2, v0
	v_mov_b32_e32 v3, v0
	v_mov_b32_e32 v4, v0
	v_mov_b32_e32 v5, v0
	v_mov_b32_e32 v6, v0
	v_mov_b32_e32 v7, v0
	v_mov_b32_e32 v16, v0
	v_mov_b32_e32 v17, v0
	v_mov_b32_e32 v18, v0
	v_mov_b32_e32 v19, v0
	v_mov_b32_e32 v20, v0
	v_mov_b32_e32 v21, v0
	v_mov_b32_e32 v22, v0
	v_mov_b32_e32 v23, v0
	v_mov_b32_e32 v34, v0
	v_mov_b32_e32 v35, v0
	v_mov_b32_e32 v36, v0
	v_mov_b32_e32 v37, v0
	v_mov_b32_e32 v38, v0
	v_mov_b32_e32 v39, v0
	v_mov_b32_e32 v40, v0
	v_mov_b32_e32 v41, v0
	v_mov_b32_e32 v50, v0
	v_mov_b32_e32 v51, v0
	v_mov_b32_e32 v52, v0
	v_mov_b32_e32 v53, v0
	v_mov_b32_e32 v54, v0
	v_mov_b32_e32 v55, v0
	v_mov_b32_e32 v56, v0
	v_mov_b32_e32 v57, v0
	v_mov_b32_e32 v8, v0
	v_mov_b32_e32 v9, v0
	v_mov_b32_e32 v10, v0
	v_mov_b32_e32 v11, v0
	v_mov_b32_e32 v12, v0
	v_mov_b32_e32 v13, v0
	v_mov_b32_e32 v14, v0
	v_mov_b32_e32 v15, v0
	v_mov_b32_e32 v24, v0
	v_mov_b32_e32 v25, v0
	v_mov_b32_e32 v26, v0
	v_mov_b32_e32 v27, v0
	v_mov_b32_e32 v28, v0
	v_mov_b32_e32 v29, v0
	v_mov_b32_e32 v30, v0
	v_mov_b32_e32 v31, v0
	v_mov_b32_e32 v42, v0
	v_mov_b32_e32 v43, v0
	v_mov_b32_e32 v44, v0
	v_mov_b32_e32 v45, v0
	v_mov_b32_e32 v46, v0
	v_mov_b32_e32 v47, v0
	v_mov_b32_e32 v48, v0
	v_mov_b32_e32 v49, v0
	v_mov_b32_e32 v58, v0
	v_mov_b32_e32 v59, v0
	v_mov_b32_e32 v60, v0
	v_mov_b32_e32 v61, v0
	v_mov_b32_e32 v62, v0
	v_mov_b32_e32 v63, v0
	v_mov_b32_e32 v64, v0
	v_mov_b32_e32 v65, v0
	v_mov_b32_e32 v74, v0
	v_mov_b32_e32 v75, v0
	v_mov_b32_e32 v76, v0
	v_mov_b32_e32 v77, v0
	v_mov_b32_e32 v78, v0
	v_mov_b32_e32 v79, v0
	v_mov_b32_e32 v80, v0
	v_mov_b32_e32 v81, v0
	v_mov_b32_e32 v114, v0
	v_mov_b32_e32 v115, v0
	v_mov_b32_e32 v116, v0
	v_mov_b32_e32 v117, v0
	v_mov_b32_e32 v118, v0
	v_mov_b32_e32 v119, v0
	v_mov_b32_e32 v120, v0
	v_mov_b32_e32 v121, v0
	v_mov_b32_e32 v130, v0
	v_mov_b32_e32 v131, v0
	v_mov_b32_e32 v132, v0
	v_mov_b32_e32 v133, v0
	v_mov_b32_e32 v134, v0
	v_mov_b32_e32 v135, v0
	v_mov_b32_e32 v136, v0
	v_mov_b32_e32 v137, v0
	v_mov_b32_e32 v146, v0
	v_mov_b32_e32 v147, v0
	v_mov_b32_e32 v148, v0
	v_mov_b32_e32 v149, v0
	v_mov_b32_e32 v150, v0
	v_mov_b32_e32 v151, v0
	v_mov_b32_e32 v152, v0
	v_mov_b32_e32 v153, v0
	v_mov_b32_e32 v98, v0
	v_mov_b32_e32 v99, v0
	v_mov_b32_e32 v100, v0
	v_mov_b32_e32 v101, v0
	v_mov_b32_e32 v102, v0
	v_mov_b32_e32 v103, v0
	v_mov_b32_e32 v104, v0
	v_mov_b32_e32 v105, v0
	v_mov_b32_e32 v122, v0
	v_mov_b32_e32 v123, v0
	v_mov_b32_e32 v124, v0
	v_mov_b32_e32 v125, v0
	v_mov_b32_e32 v126, v0
	v_mov_b32_e32 v127, v0
	v_mov_b32_e32 v128, v0
	v_mov_b32_e32 v129, v0
	v_mov_b32_e32 v138, v0
	v_mov_b32_e32 v139, v0
	v_mov_b32_e32 v140, v0
	v_mov_b32_e32 v141, v0
	v_mov_b32_e32 v142, v0
	v_mov_b32_e32 v143, v0
	v_mov_b32_e32 v144, v0
	v_mov_b32_e32 v145, v0
	v_mov_b32_e32 v154, v0
	v_mov_b32_e32 v155, v0
	v_mov_b32_e32 v156, v0
	v_mov_b32_e32 v157, v0
	v_mov_b32_e32 v158, v0
	v_mov_b32_e32 v159, v0
	v_mov_b32_e32 v160, v0
	v_mov_b32_e32 v161, v0
.Lbr_nozero:
	s_waitcnt vmcnt(0)
.LBB0_1203:
	s_add_u32 s4, s2, 0xfff80080
	s_addc_u32 s5, s3, -1
	s_add_i32 s23, 0, 0x10000
	v_add_u32_e32 v32, s23, v218
	ds_read_b128 v[66:69], v32
	ds_read_b128 v[70:73], v32 offset:1024
	ds_read_b128 v[82:85], v32 offset:2048
	ds_read_b128 v[86:89], v32 offset:3072
	s_cmp_eq_u32 s15, 28
	s_cselect_b32 s7, s17, s5
	s_cselect_b32 s6, s16, s4
	s_cselect_b32 s5, s19, s13
	s_cselect_b32 s4, s18, s9
	s_add_i32 s26, 0, 0x14000
	v_add_u32_e32 v32, s26, v218
	ds_read_b128 v[210:213], v32
	ds_read_b128 v[214:217], v32 offset:1024
	ds_read_b128 v[236:239], v32 offset:2048
	ds_read_b128 v[240:243], v32 offset:3072
	s_add_i32 m0, s36, 0xc000
	s_nop 0
	global_load_lds_dwordx4 v206, s[2:3]
	ds_read_b128 v[90:93], v235
	ds_read_b128 v[94:97], v235 offset:1024
	ds_read_b128 v[106:109], v235 offset:2048
	ds_read_b128 v[110:113], v235 offset:3072
	ds_read_b128 v[162:165], v235 offset:4096
	ds_read_b128 v[166:169], v235 offset:5120
	ds_read_b128 v[170:173], v235 offset:6144
	ds_read_b128 v[174:177], v235 offset:7168
	s_add_i32 m0, s36, 0xe000
	s_nop 0
	global_load_lds_dwordx4 v208, s[2:3]
	s_waitcnt lgkmcnt(0)
	s_barrier
	s_setprio 1
	v_mfma_f32_16x16x32_bf16 v[158:161], v[66:69], v[90:93], v[158:161]
	v_mfma_f32_16x16x32_bf16 v[154:157], v[82:85], v[90:93], v[154:157]
	v_mfma_f32_16x16x32_bf16 v[142:145], v[66:69], v[106:109], v[142:145]
	v_mfma_f32_16x16x32_bf16 v[138:141], v[82:85], v[106:109], v[138:141]
	v_mfma_f32_16x16x32_bf16 v[126:129], v[66:69], v[162:165], v[126:129]
	v_mfma_f32_16x16x32_bf16 v[122:125], v[82:85], v[162:165], v[122:125]
	v_mfma_f32_16x16x32_bf16 v[102:105], v[66:69], v[170:173], v[102:105]
	v_mfma_f32_16x16x32_bf16 v[98:101], v[82:85], v[170:173], v[98:101]
	v_mfma_f32_16x16x32_bf16 v[158:161], v[70:73], v[94:97], v[158:161]
	v_mfma_f32_16x16x32_bf16 v[154:157], v[86:89], v[94:97], v[154:157]
	v_mfma_f32_16x16x32_bf16 v[142:145], v[70:73], v[110:113], v[142:145]
	v_mfma_f32_16x16x32_bf16 v[138:141], v[86:89], v[110:113], v[138:141]
	v_mfma_f32_16x16x32_bf16 v[126:129], v[70:73], v[166:169], v[126:129]
	v_mfma_f32_16x16x32_bf16 v[122:125], v[86:89], v[166:169], v[122:125]
	v_mfma_f32_16x16x32_bf16 v[102:105], v[70:73], v[174:177], v[102:105]
	v_mfma_f32_16x16x32_bf16 v[98:101], v[86:89], v[174:177], v[98:101]
	v_mfma_f32_16x16x32_bf16 v[150:153], v[210:213], v[90:93], v[150:153]
	v_mfma_f32_16x16x32_bf16 v[90:93], v[236:239], v[90:93], v[146:149]
	v_mfma_f32_16x16x32_bf16 v[150:153], v[214:217], v[94:97], v[150:153]
	v_mfma_f32_16x16x32_bf16 v[90:93], v[240:243], v[94:97], v[90:93]
	v_mfma_f32_16x16x32_bf16 v[94:97], v[210:213], v[106:109], v[134:137]
	v_mfma_f32_16x16x32_bf16 v[106:109], v[236:239], v[106:109], v[130:133]
	v_mfma_f32_16x16x32_bf16 v[114:117], v[236:239], v[162:165], v[114:117]
	v_mfma_f32_16x16x32_bf16 v[78:81], v[210:213], v[170:173], v[78:81]
	v_mfma_f32_16x16x32_bf16 v[74:77], v[236:239], v[170:173], v[74:77]
	v_mfma_f32_16x16x32_bf16 v[94:97], v[214:217], v[110:113], v[94:97]
	v_mfma_f32_16x16x32_bf16 v[106:109], v[240:243], v[110:113], v[106:109]
	v_mfma_f32_16x16x32_bf16 v[110:113], v[210:213], v[162:165], v[118:121]
	v_mfma_f32_16x16x32_bf16 v[114:117], v[240:243], v[166:169], v[114:117]
	v_mfma_f32_16x16x32_bf16 v[78:81], v[214:217], v[174:177], v[78:81]
	v_mfma_f32_16x16x32_bf16 v[74:77], v[240:243], v[174:177], v[74:77]
	v_mfma_f32_16x16x32_bf16 v[110:113], v[214:217], v[166:169], v[110:113]
	s_setprio 0
	s_barrier
	ds_read_b128 v[118:121], v235 offset:16384
	ds_read_b128 v[130:133], v235 offset:17408
	ds_read_b128 v[134:137], v235 offset:18432
	ds_read_b128 v[146:149], v235 offset:19456
	ds_read_b128 v[162:165], v235 offset:20480
	ds_read_b128 v[166:169], v235 offset:21504
	ds_read_b128 v[170:173], v235 offset:22528
	ds_read_b128 v[174:177], v235 offset:23552
	s_add_i32 m0, s35, 0x10000
	s_nop 0
	global_load_lds_dwordx4 v184, s[4:5]
	s_add_i32 m0, s35, 0x12000
	s_nop 0
	global_load_lds_dwordx4 v180, s[4:5]
	s_mov_b32 m0, s36
	s_nop 0
	global_load_lds_dwordx4 v186, s[6:7]
	s_mov_b32 m0, s37
	s_nop 0
	global_load_lds_dwordx4 v182, s[6:7]
	s_add_u32 s24, s4, 0x80000
	s_addc_u32 s25, s5, 0
	s_add_i32 m0, s35, 0x14000
	s_nop 0
	global_load_lds_dwordx4 v184, s[24:25]
	s_add_i32 m0, s35, 0x16000
	s_nop 0
	global_load_lds_dwordx4 v180, s[24:25]
	s_waitcnt vmcnt(6)
	s_waitcnt lgkmcnt(0)
	s_barrier
	s_setprio 1
	v_mfma_f32_16x16x32_bf16 v[62:65], v[66:69], v[118:121], v[62:65]
	v_mfma_f32_16x16x32_bf16 v[58:61], v[82:85], v[118:121], v[58:61]
	v_mfma_f32_16x16x32_bf16 v[46:49], v[66:69], v[134:137], v[46:49]
	v_mfma_f32_16x16x32_bf16 v[42:45], v[82:85], v[134:137], v[42:45]
	v_mfma_f32_16x16x32_bf16 v[28:31], v[66:69], v[162:165], v[28:31]
	v_mfma_f32_16x16x32_bf16 v[24:27], v[82:85], v[162:165], v[24:27]
	v_mfma_f32_16x16x32_bf16 v[12:15], v[66:69], v[170:173], v[12:15]
	v_mfma_f32_16x16x32_bf16 v[8:11], v[82:85], v[170:173], v[8:11]
	v_mfma_f32_16x16x32_bf16 v[62:65], v[70:73], v[130:133], v[62:65]
	v_mfma_f32_16x16x32_bf16 v[58:61], v[86:89], v[130:133], v[58:61]
	v_mfma_f32_16x16x32_bf16 v[46:49], v[70:73], v[146:149], v[46:49]
	v_mfma_f32_16x16x32_bf16 v[42:45], v[86:89], v[146:149], v[42:45]
	v_mfma_f32_16x16x32_bf16 v[28:31], v[70:73], v[166:169], v[28:31]
	v_mfma_f32_16x16x32_bf16 v[24:27], v[86:89], v[166:169], v[24:27]
	v_mfma_f32_16x16x32_bf16 v[12:15], v[70:73], v[174:177], v[12:15]
	v_mfma_f32_16x16x32_bf16 v[8:11], v[86:89], v[174:177], v[8:11]
	v_mfma_f32_16x16x32_bf16 v[54:57], v[210:213], v[118:121], v[54:57]
	v_mfma_f32_16x16x32_bf16 v[50:53], v[236:239], v[118:121], v[50:53]
	v_mfma_f32_16x16x32_bf16 v[38:41], v[210:213], v[134:137], v[38:41]
	v_mfma_f32_16x16x32_bf16 v[34:37], v[236:239], v[134:137], v[34:37]
	v_mfma_f32_16x16x32_bf16 v[20:23], v[210:213], v[162:165], v[20:23]
	v_mfma_f32_16x16x32_bf16 v[16:19], v[236:239], v[162:165], v[16:19]
	v_mfma_f32_16x16x32_bf16 v[4:7], v[210:213], v[170:173], v[4:7]
	v_mfma_f32_16x16x32_bf16 v[0:3], v[236:239], v[170:173], v[0:3]
	v_mfma_f32_16x16x32_bf16 v[54:57], v[214:217], v[130:133], v[54:57]
	v_mfma_f32_16x16x32_bf16 v[50:53], v[240:243], v[130:133], v[50:53]
	v_mfma_f32_16x16x32_bf16 v[38:41], v[214:217], v[146:149], v[38:41]
	v_mfma_f32_16x16x32_bf16 v[34:37], v[240:243], v[146:149], v[34:37]
	v_mfma_f32_16x16x32_bf16 v[20:23], v[214:217], v[166:169], v[20:23]
	v_mfma_f32_16x16x32_bf16 v[16:19], v[240:243], v[166:169], v[16:19]
	v_mfma_f32_16x16x32_bf16 v[4:7], v[214:217], v[174:177], v[4:7]
	v_mfma_f32_16x16x32_bf16 v[0:3], v[240:243], v[174:177], v[0:3]
	s_setprio 0
	s_add_i32 s23, 0, 0x18000
	v_add_u32_e32 v32, s23, v218
	s_barrier
	ds_read_b128 v[66:69], v32
	ds_read_b128 v[70:73], v32 offset:1024
	ds_read_b128 v[82:85], v32 offset:2048
	ds_read_b128 v[86:89], v32 offset:3072
	s_add_u32 s6, s6, 0x80000
	s_addc_u32 s7, s7, 0
	s_add_i32 s24, 0, 0x1c000
	v_add_u32_e32 v32, s24, v218
	ds_read_b128 v[236:239], v32
	ds_read_b128 v[240:243], v32 offset:1024
	ds_read_b128 v[244:247], v32 offset:2048
	ds_read_b128 v[248:251], v32 offset:3072
	s_mov_b32 m0, s38
	s_nop 0
	global_load_lds_dwordx4 v186, s[6:7]
	ds_read_b128 v[118:121], v235 offset:32768
	ds_read_b128 v[130:133], v235 offset:33792
	ds_read_b128 v[162:165], v235 offset:34816
	ds_read_b128 v[166:169], v235 offset:35840
	ds_read_b128 v[170:173], v235 offset:36864
	ds_read_b128 v[174:177], v235 offset:37888
	ds_read_b128 v[210:213], v235 offset:38912
	ds_read_b128 v[214:217], v235 offset:39936
	s_mov_b32 m0, s39
	s_nop 0
	global_load_lds_dwordx4 v182, s[6:7]
	s_waitcnt lgkmcnt(0)
	s_barrier
	s_setprio 1
	v_mfma_f32_16x16x32_bf16 v[134:137], v[66:69], v[118:121], v[158:161]
	v_mfma_f32_16x16x32_bf16 v[158:161], v[70:73], v[130:133], v[134:137]
	v_mfma_f32_16x16x32_bf16 v[134:137], v[82:85], v[118:121], v[154:157]
	v_mfma_f32_16x16x32_bf16 v[154:157], v[86:89], v[130:133], v[134:137]
	v_mfma_f32_16x16x32_bf16 v[134:137], v[66:69], v[162:165], v[142:145]
	v_mfma_f32_16x16x32_bf16 v[142:145], v[70:73], v[166:169], v[134:137]
	v_mfma_f32_16x16x32_bf16 v[134:137], v[82:85], v[162:165], v[138:141]
	v_mfma_f32_16x16x32_bf16 v[126:129], v[66:69], v[170:173], v[126:129]
	v_mfma_f32_16x16x32_bf16 v[122:125], v[82:85], v[170:173], v[122:125]
	v_mfma_f32_16x16x32_bf16 v[102:105], v[66:69], v[210:213], v[102:105]
	v_mfma_f32_16x16x32_bf16 v[98:101], v[82:85], v[210:213], v[98:101]
	v_mfma_f32_16x16x32_bf16 v[138:141], v[86:89], v[166:169], v[134:137]
	v_mfma_f32_16x16x32_bf16 v[126:129], v[70:73], v[174:177], v[126:129]
	v_mfma_f32_16x16x32_bf16 v[122:125], v[86:89], v[174:177], v[122:125]
	v_mfma_f32_16x16x32_bf16 v[102:105], v[70:73], v[214:217], v[102:105]
	v_mfma_f32_16x16x32_bf16 v[98:101], v[86:89], v[214:217], v[98:101]
	v_mfma_f32_16x16x32_bf16 v[90:93], v[244:247], v[118:121], v[90:93]
	v_mfma_f32_16x16x32_bf16 v[134:137], v[236:239], v[118:121], v[150:153]
	v_mfma_f32_16x16x32_bf16 v[146:149], v[248:251], v[130:133], v[90:93]
	v_mfma_f32_16x16x32_bf16 v[90:93], v[236:239], v[162:165], v[94:97]
	v_mfma_f32_16x16x32_bf16 v[150:153], v[240:243], v[130:133], v[134:137]
	v_mfma_f32_16x16x32_bf16 v[134:137], v[240:243], v[166:169], v[90:93]
	v_mfma_f32_16x16x32_bf16 v[90:93], v[244:247], v[162:165], v[106:109]
	v_mfma_f32_16x16x32_bf16 v[130:133], v[248:251], v[166:169], v[90:93]
	v_mfma_f32_16x16x32_bf16 v[90:93], v[236:239], v[170:173], v[110:113]
	v_mfma_f32_16x16x32_bf16 v[118:121], v[240:243], v[174:177], v[90:93]
	v_mfma_f32_16x16x32_bf16 v[90:93], v[244:247], v[170:173], v[114:117]
	v_mfma_f32_16x16x32_bf16 v[78:81], v[236:239], v[210:213], v[78:81]
	v_mfma_f32_16x16x32_bf16 v[74:77], v[244:247], v[210:213], v[74:77]
	v_mfma_f32_16x16x32_bf16 v[114:117], v[248:251], v[174:177], v[90:93]
	v_mfma_f32_16x16x32_bf16 v[78:81], v[240:243], v[214:217], v[78:81]
	v_mfma_f32_16x16x32_bf16 v[74:77], v[248:251], v[214:217], v[74:77]
	s_setprio 0
	s_barrier
	ds_read_b128 v[90:93], v235 offset:49152
	ds_read_b128 v[94:97], v235 offset:50176
	ds_read_b128 v[106:109], v235 offset:51200
	ds_read_b128 v[110:113], v235 offset:52224
	ds_read_b128 v[162:165], v235 offset:53248
	ds_read_b128 v[166:169], v235 offset:54272
	ds_read_b128 v[170:173], v235 offset:55296
	ds_read_b128 v[174:177], v235 offset:56320
	s_add_u32 s4, s4, 0x80
	s_addc_u32 s5, s5, 0
	s_add_i32 m0, s35, 0x18000
	s_nop 0
	global_load_lds_dwordx4 v184, s[4:5]
	s_add_i32 m0, s35, 0x1a000
	s_nop 0
	global_load_lds_dwordx4 v180, s[4:5]
	s_add_u32 s6, s6, 0xfff80080
	s_addc_u32 s7, s7, -1
	s_mov_b32 m0, s40
	s_nop 0
	global_load_lds_dwordx4 v186, s[6:7]
	s_mov_b32 m0, s41
	s_nop 0
	global_load_lds_dwordx4 v182, s[6:7]
	s_add_u32 s4, s4, 0x80000
	s_addc_u32 s5, s5, 0
	s_add_i32 m0, s35, 0x1c000
	s_nop 0
	global_load_lds_dwordx4 v184, s[4:5]
	s_add_i32 m0, s35, 0x1e000
	s_nop 0
	global_load_lds_dwordx4 v180, s[4:5]
	s_waitcnt vmcnt(6)
	s_waitcnt lgkmcnt(0)
	s_barrier
	s_setprio 1
	v_mfma_f32_16x16x32_bf16 v[62:65], v[66:69], v[90:93], v[62:65]
	v_mfma_f32_16x16x32_bf16 v[58:61], v[82:85], v[90:93], v[58:61]
	v_mfma_f32_16x16x32_bf16 v[46:49], v[66:69], v[106:109], v[46:49]
	v_mfma_f32_16x16x32_bf16 v[42:45], v[82:85], v[106:109], v[42:45]
	v_mfma_f32_16x16x32_bf16 v[28:31], v[66:69], v[162:165], v[28:31]
	v_mfma_f32_16x16x32_bf16 v[24:27], v[82:85], v[162:165], v[24:27]
	v_mfma_f32_16x16x32_bf16 v[12:15], v[66:69], v[170:173], v[12:15]
	v_mfma_f32_16x16x32_bf16 v[8:11], v[82:85], v[170:173], v[8:11]
	v_mfma_f32_16x16x32_bf16 v[62:65], v[70:73], v[94:97], v[62:65]
	v_mfma_f32_16x16x32_bf16 v[58:61], v[86:89], v[94:97], v[58:61]
	v_mfma_f32_16x16x32_bf16 v[46:49], v[70:73], v[110:113], v[46:49]
	v_mfma_f32_16x16x32_bf16 v[42:45], v[86:89], v[110:113], v[42:45]
	v_mfma_f32_16x16x32_bf16 v[28:31], v[70:73], v[166:169], v[28:31]
	v_mfma_f32_16x16x32_bf16 v[24:27], v[86:89], v[166:169], v[24:27]
	v_mfma_f32_16x16x32_bf16 v[12:15], v[70:73], v[174:177], v[12:15]
	v_mfma_f32_16x16x32_bf16 v[8:11], v[86:89], v[174:177], v[8:11]
	v_mfma_f32_16x16x32_bf16 v[54:57], v[236:239], v[90:93], v[54:57]
	v_mfma_f32_16x16x32_bf16 v[50:53], v[244:247], v[90:93], v[50:53]
	v_mfma_f32_16x16x32_bf16 v[38:41], v[236:239], v[106:109], v[38:41]
	v_mfma_f32_16x16x32_bf16 v[34:37], v[244:247], v[106:109], v[34:37]
	v_mfma_f32_16x16x32_bf16 v[20:23], v[236:239], v[162:165], v[20:23]
	v_mfma_f32_16x16x32_bf16 v[16:19], v[244:247], v[162:165], v[16:19]
	v_mfma_f32_16x16x32_bf16 v[4:7], v[236:239], v[170:173], v[4:7]
	v_mfma_f32_16x16x32_bf16 v[0:3], v[244:247], v[170:173], v[0:3]
	v_mfma_f32_16x16x32_bf16 v[54:57], v[240:243], v[94:97], v[54:57]
	v_mfma_f32_16x16x32_bf16 v[50:53], v[248:251], v[94:97], v[50:53]
	v_mfma_f32_16x16x32_bf16 v[38:41], v[240:243], v[110:113], v[38:41]
	v_mfma_f32_16x16x32_bf16 v[34:37], v[248:251], v[110:113], v[34:37]
	v_mfma_f32_16x16x32_bf16 v[20:23], v[240:243], v[166:169], v[20:23]
	v_mfma_f32_16x16x32_bf16 v[16:19], v[248:251], v[166:169], v[16:19]
	v_mfma_f32_16x16x32_bf16 v[4:7], v[240:243], v[174:177], v[4:7]
	v_mfma_f32_16x16x32_bf16 v[0:3], v[248:251], v[174:177], v[0:3]
	s_setprio 0
	s_add_i32 s15, s15, 2
	s_add_u32 s2, s2, 0x100
	s_addc_u32 s3, s3, 0
	s_add_u32 s9, s9, 0x100
	s_addc_u32 s13, s13, 0
	s_cmp_gt_u32 s15, 29
	s_barrier
	s_cbranch_scc0 .LBB0_1203
	v_mul_u32_u24_e32 v226, 0x3000, v189
	v_lshl_add_u32 v226, v188, 1, v226
	s_mul_i32 s26, s21, 0x300000
	s_lshl_b32 s2, s22, 12
	s_add_i32 s26, s26, s2
	s_lshl_b32 s2, s20, 9
	s_add_i32 s26, s26, s2
	s_add_i32 s26, s26, 0x37f51000
	s_add_u32 s26, s76, s26
	s_addc_u32 s27, s77, 0
	s_cmp_eq_u32 s22, 2
	s_cbranch_scc1 .Lbr_epi_final
	s_add_u32 s2, s26, 0
	s_addc_u32 s3, s27, 0
	s_add_u32 s4, s2, 0x30000
	s_addc_u32 s5, s3, 0
	s_add_u32 s6, s2, 0x1000
	s_addc_u32 s7, s3, 0
	s_add_u32 s24, s4, 0x1000
	s_addc_u32 s25, s5, 0
	global_load_dwordx4 v[66:69], v226, s[2:3]
	global_load_dwordx4 v[70:73], v226, s[6:7]
	global_load_dwordx4 v[82:85], v226, s[2:3] offset:256
	global_load_dwordx4 v[86:89], v226, s[6:7] offset:256
	global_load_dwordx4 v[90:93], v226, s[4:5]
	global_load_dwordx4 v[94:97], v226, s[24:25]
	global_load_dwordx4 v[106:109], v226, s[4:5] offset:256
	global_load_dwordx4 v[110:113], v226, s[24:25] offset:256
	s_add_u32 s2, s26, 0x60000
	s_addc_u32 s3, s27, 0
	s_add_u32 s4, s2, 0x30000
	s_addc_u32 s5, s3, 0
	s_add_u32 s6, s2, 0x1000
	s_addc_u32 s7, s3, 0
	s_add_u32 s24, s4, 0x1000
	s_addc_u32 s25, s5, 0
	global_load_dwordx4 v[162:165], v226, s[2:3]
	global_load_dwordx4 v[166:169], v226, s[6:7]
	global_load_dwordx4 v[170:173], v226, s[2:3] offset:256
	global_load_dwordx4 v[174:177], v226, s[6:7] offset:256
	global_load_dwordx4 v[210:213], v226, s[4:5]
	global_load_dwordx4 v[214:217], v226, s[24:25]
	global_load_dwordx4 v[236:239], v226, s[4:5] offset:256
	global_load_dwordx4 v[240:243], v226, s[24:25] offset:256
	s_waitcnt vmcnt(8)
	v_lshlrev_b32_e32 v246, 16, v70
	v_and_b32_e32 v247, 0xffff0000, v70
	v_lshlrev_b32_e32 v250, 16, v71
	v_and_b32_e32 v251, 0xffff0000, v71
	v_max_f32_e32 v246, 0x0da24260, v246
	v_max_f32_e32 v247, 0x0da24260, v247
	v_max_f32_e32 v250, 0x0da24260, v250
	v_max_f32_e32 v251, 0x0da24260, v251
	v_rcp_f32_e32 v246, v246
	v_rcp_f32_e32 v247, v247
	v_rcp_f32_e32 v250, v250
	v_rcp_f32_e32 v251, v251
	v_lshlrev_b32_e32 v244, 16, v66
	v_and_b32_e32 v245, 0xffff0000, v66
	v_lshlrev_b32_e32 v248, 16, v67
	v_and_b32_e32 v249, 0xffff0000, v67
	v_pk_mul_f32 v[158:159], v[158:159], v[244:245]
	v_pk_mul_f32 v[160:161], v[160:161], v[248:249]
	v_pk_mul_f32 v[158:159], v[158:159], v[246:247]
	v_pk_mul_f32 v[160:161], v[160:161], v[250:251]
	v_lshlrev_b32_e32 v246, 16, v72
	v_and_b32_e32 v247, 0xffff0000, v72
	v_lshlrev_b32_e32 v250, 16, v73
	v_and_b32_e32 v251, 0xffff0000, v73
	v_max_f32_e32 v246, 0x0da24260, v246
	v_max_f32_e32 v247, 0x0da24260, v247
	v_max_f32_e32 v250, 0x0da24260, v250
	v_max_f32_e32 v251, 0x0da24260, v251
	v_rcp_f32_e32 v246, v246
	v_rcp_f32_e32 v247, v247
	v_rcp_f32_e32 v250, v250
	v_rcp_f32_e32 v251, v251
	v_lshlrev_b32_e32 v244, 16, v68
	v_and_b32_e32 v245, 0xffff0000, v68
	v_lshlrev_b32_e32 v248, 16, v69
	v_and_b32_e32 v249, 0xffff0000, v69
	v_pk_mul_f32 v[154:155], v[154:155], v[244:245]
	v_pk_mul_f32 v[156:157], v[156:157], v[248:249]
	v_pk_mul_f32 v[154:155], v[154:155], v[246:247]
	v_pk_mul_f32 v[156:157], v[156:157], v[250:251]
	v_lshlrev_b32_e32 v246, 16, v86
	v_and_b32_e32 v247, 0xffff0000, v86
	v_lshlrev_b32_e32 v250, 16, v87
	v_and_b32_e32 v251, 0xffff0000, v87
	v_max_f32_e32 v246, 0x0da24260, v246
	v_max_f32_e32 v247, 0x0da24260, v247
	v_max_f32_e32 v250, 0x0da24260, v250
	v_max_f32_e32 v251, 0x0da24260, v251
	v_rcp_f32_e32 v246, v246
	v_rcp_f32_e32 v247, v247
	v_rcp_f32_e32 v250, v250
	v_rcp_f32_e32 v251, v251
	v_lshlrev_b32_e32 v244, 16, v82
	v_and_b32_e32 v245, 0xffff0000, v82
	v_lshlrev_b32_e32 v248, 16, v83
	v_and_b32_e32 v249, 0xffff0000, v83
	v_pk_mul_f32 v[150:151], v[150:151], v[244:245]
	v_pk_mul_f32 v[152:153], v[152:153], v[248:249]
	v_pk_mul_f32 v[150:151], v[150:151], v[246:247]
	v_pk_mul_f32 v[152:153], v[152:153], v[250:251]
	v_lshlrev_b32_e32 v246, 16, v88
	v_and_b32_e32 v247, 0xffff0000, v88
	v_lshlrev_b32_e32 v250, 16, v89
	v_and_b32_e32 v251, 0xffff0000, v89
	v_max_f32_e32 v246, 0x0da24260, v246
	v_max_f32_e32 v247, 0x0da24260, v247
	v_max_f32_e32 v250, 0x0da24260, v250
	v_max_f32_e32 v251, 0x0da24260, v251
	v_rcp_f32_e32 v246, v246
	v_rcp_f32_e32 v247, v247
	v_rcp_f32_e32 v250, v250
	v_rcp_f32_e32 v251, v251
	v_lshlrev_b32_e32 v244, 16, v84
	v_and_b32_e32 v245, 0xffff0000, v84
	v_lshlrev_b32_e32 v248, 16, v85
	v_and_b32_e32 v249, 0xffff0000, v85
	v_pk_mul_f32 v[146:147], v[146:147], v[244:245]
	v_pk_mul_f32 v[148:149], v[148:149], v[248:249]
	v_pk_mul_f32 v[146:147], v[146:147], v[246:247]
	v_pk_mul_f32 v[148:149], v[148:149], v[250:251]
	v_lshlrev_b32_e32 v246, 16, v94
	v_and_b32_e32 v247, 0xffff0000, v94
	v_lshlrev_b32_e32 v250, 16, v95
	v_and_b32_e32 v251, 0xffff0000, v95
	v_max_f32_e32 v246, 0x0da24260, v246
	v_max_f32_e32 v247, 0x0da24260, v247
	v_max_f32_e32 v250, 0x0da24260, v250
	v_max_f32_e32 v251, 0x0da24260, v251
	v_rcp_f32_e32 v246, v246
	v_rcp_f32_e32 v247, v247
	v_rcp_f32_e32 v250, v250
	v_rcp_f32_e32 v251, v251
	v_lshlrev_b32_e32 v244, 16, v90
	v_and_b32_e32 v245, 0xffff0000, v90
	v_lshlrev_b32_e32 v248, 16, v91
	v_and_b32_e32 v249, 0xffff0000, v91
	v_pk_mul_f32 v[142:143], v[142:143], v[244:245]
	v_pk_mul_f32 v[144:145], v[144:145], v[248:249]
	v_pk_mul_f32 v[142:143], v[142:143], v[246:247]
	v_pk_mul_f32 v[144:145], v[144:145], v[250:251]
	v_lshlrev_b32_e32 v246, 16, v96
	v_and_b32_e32 v247, 0xffff0000, v96
	v_lshlrev_b32_e32 v250, 16, v97
	v_and_b32_e32 v251, 0xffff0000, v97
	v_max_f32_e32 v246, 0x0da24260, v246
	v_max_f32_e32 v247, 0x0da24260, v247
	v_max_f32_e32 v250, 0x0da24260, v250
	v_max_f32_e32 v251, 0x0da24260, v251
	v_rcp_f32_e32 v246, v246
	v_rcp_f32_e32 v247, v247
	v_rcp_f32_e32 v250, v250
	v_rcp_f32_e32 v251, v251
	v_lshlrev_b32_e32 v244, 16, v92
	v_and_b32_e32 v245, 0xffff0000, v92
	v_lshlrev_b32_e32 v248, 16, v93
	v_and_b32_e32 v249, 0xffff0000, v93
	v_pk_mul_f32 v[138:139], v[138:139], v[244:245]
	v_pk_mul_f32 v[140:141], v[140:141], v[248:249]
	v_pk_mul_f32 v[138:139], v[138:139], v[246:247]
	v_pk_mul_f32 v[140:141], v[140:141], v[250:251]
	v_lshlrev_b32_e32 v246, 16, v110
	v_and_b32_e32 v247, 0xffff0000, v110
	v_lshlrev_b32_e32 v250, 16, v111
	v_and_b32_e32 v251, 0xffff0000, v111
	v_max_f32_e32 v246, 0x0da24260, v246
	v_max_f32_e32 v247, 0x0da24260, v247
	v_max_f32_e32 v250, 0x0da24260, v250
	v_max_f32_e32 v251, 0x0da24260, v251
	v_rcp_f32_e32 v246, v246
	v_rcp_f32_e32 v247, v247
	v_rcp_f32_e32 v250, v250
	v_rcp_f32_e32 v251, v251
	v_lshlrev_b32_e32 v244, 16, v106
	v_and_b32_e32 v245, 0xffff0000, v106
	v_lshlrev_b32_e32 v248, 16, v107
	v_and_b32_e32 v249, 0xffff0000, v107
	v_pk_mul_f32 v[134:135], v[134:135], v[244:245]
	v_pk_mul_f32 v[136:137], v[136:137], v[248:249]
	v_pk_mul_f32 v[134:135], v[134:135], v[246:247]
	v_pk_mul_f32 v[136:137], v[136:137], v[250:251]
	v_lshlrev_b32_e32 v246, 16, v112
	v_and_b32_e32 v247, 0xffff0000, v112
	v_lshlrev_b32_e32 v250, 16, v113
	v_and_b32_e32 v251, 0xffff0000, v113
	v_max_f32_e32 v246, 0x0da24260, v246
	v_max_f32_e32 v247, 0x0da24260, v247
	v_max_f32_e32 v250, 0x0da24260, v250
	v_max_f32_e32 v251, 0x0da24260, v251
	v_rcp_f32_e32 v246, v246
	v_rcp_f32_e32 v247, v247
	v_rcp_f32_e32 v250, v250
	v_rcp_f32_e32 v251, v251
	v_lshlrev_b32_e32 v244, 16, v108
	v_and_b32_e32 v245, 0xffff0000, v108
	v_lshlrev_b32_e32 v248, 16, v109
	v_and_b32_e32 v249, 0xffff0000, v109
	v_pk_mul_f32 v[130:131], v[130:131], v[244:245]
	v_pk_mul_f32 v[132:133], v[132:133], v[248:249]
	v_pk_mul_f32 v[130:131], v[130:131], v[246:247]
	v_pk_mul_f32 v[132:133], v[132:133], v[250:251]
	s_add_u32 s2, s26, 0x180000
	s_addc_u32 s3, s27, 0
	s_add_u32 s4, s2, 0x30000
	s_addc_u32 s5, s3, 0
	s_add_u32 s6, s2, 0x1000
	s_addc_u32 s7, s3, 0
	s_add_u32 s24, s4, 0x1000
	s_addc_u32 s25, s5, 0
	global_load_dwordx4 v[66:69], v226, s[2:3]
	global_load_dwordx4 v[70:73], v226, s[6:7]
	global_load_dwordx4 v[82:85], v226, s[2:3] offset:256
	global_load_dwordx4 v[86:89], v226, s[6:7] offset:256
	global_load_dwordx4 v[90:93], v226, s[4:5]
	global_load_dwordx4 v[94:97], v226, s[24:25]
	global_load_dwordx4 v[106:109], v226, s[4:5] offset:256
	global_load_dwordx4 v[110:113], v226, s[24:25] offset:256
	s_waitcnt vmcnt(8)
	v_lshlrev_b32_e32 v246, 16, v166
	v_and_b32_e32 v247, 0xffff0000, v166
	v_lshlrev_b32_e32 v250, 16, v167
	v_and_b32_e32 v251, 0xffff0000, v167
	v_max_f32_e32 v246, 0x0da24260, v246
	v_max_f32_e32 v247, 0x0da24260, v247
	v_max_f32_e32 v250, 0x0da24260, v250
	v_max_f32_e32 v251, 0x0da24260, v251
	v_rcp_f32_e32 v246, v246
	v_rcp_f32_e32 v247, v247
	v_rcp_f32_e32 v250, v250
	v_rcp_f32_e32 v251, v251
	v_lshlrev_b32_e32 v244, 16, v162
	v_and_b32_e32 v245, 0xffff0000, v162
	v_lshlrev_b32_e32 v248, 16, v163
	v_and_b32_e32 v249, 0xffff0000, v163
	v_pk_mul_f32 v[126:127], v[126:127], v[244:245]
	v_pk_mul_f32 v[128:129], v[128:129], v[248:249]
	v_pk_mul_f32 v[126:127], v[126:127], v[246:247]
	v_pk_mul_f32 v[128:129], v[128:129], v[250:251]
	v_lshlrev_b32_e32 v246, 16, v168
	v_and_b32_e32 v247, 0xffff0000, v168
	v_lshlrev_b32_e32 v250, 16, v169
	v_and_b32_e32 v251, 0xffff0000, v169
	v_max_f32_e32 v246, 0x0da24260, v246
	v_max_f32_e32 v247, 0x0da24260, v247
	v_max_f32_e32 v250, 0x0da24260, v250
	v_max_f32_e32 v251, 0x0da24260, v251
	v_rcp_f32_e32 v246, v246
	v_rcp_f32_e32 v247, v247
	v_rcp_f32_e32 v250, v250
	v_rcp_f32_e32 v251, v251
	v_lshlrev_b32_e32 v244, 16, v164
	v_and_b32_e32 v245, 0xffff0000, v164
	v_lshlrev_b32_e32 v248, 16, v165
	v_and_b32_e32 v249, 0xffff0000, v165
	v_pk_mul_f32 v[122:123], v[122:123], v[244:245]
	v_pk_mul_f32 v[124:125], v[124:125], v[248:249]
	v_pk_mul_f32 v[122:123], v[122:123], v[246:247]
	v_pk_mul_f32 v[124:125], v[124:125], v[250:251]
	v_lshlrev_b32_e32 v246, 16, v174
	v_and_b32_e32 v247, 0xffff0000, v174
	v_lshlrev_b32_e32 v250, 16, v175
	v_and_b32_e32 v251, 0xffff0000, v175
	v_max_f32_e32 v246, 0x0da24260, v246
	v_max_f32_e32 v247, 0x0da24260, v247
	v_max_f32_e32 v250, 0x0da24260, v250
	v_max_f32_e32 v251, 0x0da24260, v251
	v_rcp_f32_e32 v246, v246
	v_rcp_f32_e32 v247, v247
	v_rcp_f32_e32 v250, v250
	v_rcp_f32_e32 v251, v251
	v_lshlrev_b32_e32 v244, 16, v170
	v_and_b32_e32 v245, 0xffff0000, v170
	v_lshlrev_b32_e32 v248, 16, v171
	v_and_b32_e32 v249, 0xffff0000, v171
	v_pk_mul_f32 v[118:119], v[118:119], v[244:245]
	v_pk_mul_f32 v[120:121], v[120:121], v[248:249]
	v_pk_mul_f32 v[118:119], v[118:119], v[246:247]
	v_pk_mul_f32 v[120:121], v[120:121], v[250:251]
	v_lshlrev_b32_e32 v246, 16, v176
	v_and_b32_e32 v247, 0xffff0000, v176
	v_lshlrev_b32_e32 v250, 16, v177
	v_and_b32_e32 v251, 0xffff0000, v177
	v_max_f32_e32 v246, 0x0da24260, v246
	v_max_f32_e32 v247, 0x0da24260, v247
	v_max_f32_e32 v250, 0x0da24260, v250
	v_max_f32_e32 v251, 0x0da24260, v251
	v_rcp_f32_e32 v246, v246
	v_rcp_f32_e32 v247, v247
	v_rcp_f32_e32 v250, v250
	v_rcp_f32_e32 v251, v251
	v_lshlrev_b32_e32 v244, 16, v172
	v_and_b32_e32 v245, 0xffff0000, v172
	v_lshlrev_b32_e32 v248, 16, v173
	v_and_b32_e32 v249, 0xffff0000, v173
	v_pk_mul_f32 v[114:115], v[114:115], v[244:245]
	v_pk_mul_f32 v[116:117], v[116:117], v[248:249]
	v_pk_mul_f32 v[114:115], v[114:115], v[246:247]
	v_pk_mul_f32 v[116:117], v[116:117], v[250:251]
	v_lshlrev_b32_e32 v246, 16, v214
	v_and_b32_e32 v247, 0xffff0000, v214
	v_lshlrev_b32_e32 v250, 16, v215
	v_and_b32_e32 v251, 0xffff0000, v215
	v_max_f32_e32 v246, 0x0da24260, v246
	v_max_f32_e32 v247, 0x0da24260, v247
	v_max_f32_e32 v250, 0x0da24260, v250
	v_max_f32_e32 v251, 0x0da24260, v251
	v_rcp_f32_e32 v246, v246
	v_rcp_f32_e32 v247, v247
	v_rcp_f32_e32 v250, v250
	v_rcp_f32_e32 v251, v251
	v_lshlrev_b32_e32 v244, 16, v210
	v_and_b32_e32 v245, 0xffff0000, v210
	v_lshlrev_b32_e32 v248, 16, v211
	v_and_b32_e32 v249, 0xffff0000, v211
	v_pk_mul_f32 v[102:103], v[102:103], v[244:245]
	v_pk_mul_f32 v[104:105], v[104:105], v[248:249]
	v_pk_mul_f32 v[102:103], v[102:103], v[246:247]
	v_pk_mul_f32 v[104:105], v[104:105], v[250:251]
	v_lshlrev_b32_e32 v246, 16, v216
	v_and_b32_e32 v247, 0xffff0000, v216
	v_lshlrev_b32_e32 v250, 16, v217
	v_and_b32_e32 v251, 0xffff0000, v217
	v_max_f32_e32 v246, 0x0da24260, v246
	v_max_f32_e32 v247, 0x0da24260, v247
	v_max_f32_e32 v250, 0x0da24260, v250
	v_max_f32_e32 v251, 0x0da24260, v251
	v_rcp_f32_e32 v246, v246
	v_rcp_f32_e32 v247, v247
	v_rcp_f32_e32 v250, v250
	v_rcp_f32_e32 v251, v251
	v_lshlrev_b32_e32 v244, 16, v212
	v_and_b32_e32 v245, 0xffff0000, v212
	v_lshlrev_b32_e32 v248, 16, v213
	v_and_b32_e32 v249, 0xffff0000, v213
	v_pk_mul_f32 v[98:99], v[98:99], v[244:245]
	v_pk_mul_f32 v[100:101], v[100:101], v[248:249]
	v_pk_mul_f32 v[98:99], v[98:99], v[246:247]
	v_pk_mul_f32 v[100:101], v[100:101], v[250:251]
	v_lshlrev_b32_e32 v246, 16, v240
	v_and_b32_e32 v247, 0xffff0000, v240
	v_lshlrev_b32_e32 v250, 16, v241
	v_and_b32_e32 v251, 0xffff0000, v241
	v_max_f32_e32 v246, 0x0da24260, v246
	v_max_f32_e32 v247, 0x0da24260, v247
	v_max_f32_e32 v250, 0x0da24260, v250
	v_max_f32_e32 v251, 0x0da24260, v251
	v_rcp_f32_e32 v246, v246
	v_rcp_f32_e32 v247, v247
	v_rcp_f32_e32 v250, v250
	v_rcp_f32_e32 v251, v251
	v_lshlrev_b32_e32 v244, 16, v236
	v_and_b32_e32 v245, 0xffff0000, v236
	v_lshlrev_b32_e32 v248, 16, v237
	v_and_b32_e32 v249, 0xffff0000, v237
	v_pk_mul_f32 v[78:79], v[78:79], v[244:245]
	v_pk_mul_f32 v[80:81], v[80:81], v[248:249]
	v_pk_mul_f32 v[78:79], v[78:79], v[246:247]
	v_pk_mul_f32 v[80:81], v[80:81], v[250:251]
	v_lshlrev_b32_e32 v246, 16, v242
	v_and_b32_e32 v247, 0xffff0000, v242
	v_lshlrev_b32_e32 v250, 16, v243
	v_and_b32_e32 v251, 0xffff0000, v243
	v_max_f32_e32 v246, 0x0da24260, v246
	v_max_f32_e32 v247, 0x0da24260, v247
	v_max_f32_e32 v250, 0x0da24260, v250
	v_max_f32_e32 v251, 0x0da24260, v251
	v_rcp_f32_e32 v246, v246
	v_rcp_f32_e32 v247, v247
	v_rcp_f32_e32 v250, v250
	v_rcp_f32_e32 v251, v251
	v_lshlrev_b32_e32 v244, 16, v238
	v_and_b32_e32 v245, 0xffff0000, v238
	v_lshlrev_b32_e32 v248, 16, v239
	v_and_b32_e32 v249, 0xffff0000, v239
	v_pk_mul_f32 v[74:75], v[74:75], v[244:245]
	v_pk_mul_f32 v[76:77], v[76:77], v[248:249]
	v_pk_mul_f32 v[74:75], v[74:75], v[246:247]
	v_pk_mul_f32 v[76:77], v[76:77], v[250:251]
	s_add_u32 s2, s26, 0x1e0000
	s_addc_u32 s3, s27, 0
	s_add_u32 s4, s2, 0x30000
	s_addc_u32 s5, s3, 0
	s_add_u32 s6, s2, 0x1000
	s_addc_u32 s7, s3, 0
	s_add_u32 s24, s4, 0x1000
	s_addc_u32 s25, s5, 0
	global_load_dwordx4 v[162:165], v226, s[2:3]
	global_load_dwordx4 v[166:169], v226, s[6:7]
	global_load_dwordx4 v[170:173], v226, s[2:3] offset:256
	global_load_dwordx4 v[174:177], v226, s[6:7] offset:256
	global_load_dwordx4 v[210:213], v226, s[4:5]
	global_load_dwordx4 v[214:217], v226, s[24:25]
	global_load_dwordx4 v[236:239], v226, s[4:5] offset:256
	global_load_dwordx4 v[240:243], v226, s[24:25] offset:256
	s_waitcnt vmcnt(8)
	v_lshlrev_b32_e32 v246, 16, v70
	v_and_b32_e32 v247, 0xffff0000, v70
	v_lshlrev_b32_e32 v250, 16, v71
	v_and_b32_e32 v251, 0xffff0000, v71
	v_max_f32_e32 v246, 0x0da24260, v246
	v_max_f32_e32 v247, 0x0da24260, v247
	v_max_f32_e32 v250, 0x0da24260, v250
	v_max_f32_e32 v251, 0x0da24260, v251
	v_rcp_f32_e32 v246, v246
	v_rcp_f32_e32 v247, v247
	v_rcp_f32_e32 v250, v250
	v_rcp_f32_e32 v251, v251
	v_lshlrev_b32_e32 v244, 16, v66
	v_and_b32_e32 v245, 0xffff0000, v66
	v_lshlrev_b32_e32 v248, 16, v67
	v_and_b32_e32 v249, 0xffff0000, v67
	v_pk_mul_f32 v[62:63], v[62:63], v[244:245]
	v_pk_mul_f32 v[64:65], v[64:65], v[248:249]
	v_pk_mul_f32 v[62:63], v[62:63], v[246:247]
	v_pk_mul_f32 v[64:65], v[64:65], v[250:251]
	v_lshlrev_b32_e32 v246, 16, v72
	v_and_b32_e32 v247, 0xffff0000, v72
	v_lshlrev_b32_e32 v250, 16, v73
	v_and_b32_e32 v251, 0xffff0000, v73
	v_max_f32_e32 v246, 0x0da24260, v246
	v_max_f32_e32 v247, 0x0da24260, v247
	v_max_f32_e32 v250, 0x0da24260, v250
	v_max_f32_e32 v251, 0x0da24260, v251
	v_rcp_f32_e32 v246, v246
	v_rcp_f32_e32 v247, v247
	v_rcp_f32_e32 v250, v250
	v_rcp_f32_e32 v251, v251
	v_lshlrev_b32_e32 v244, 16, v68
	v_and_b32_e32 v245, 0xffff0000, v68
	v_lshlrev_b32_e32 v248, 16, v69
	v_and_b32_e32 v249, 0xffff0000, v69
	v_pk_mul_f32 v[58:59], v[58:59], v[244:245]
	v_pk_mul_f32 v[60:61], v[60:61], v[248:249]
	v_pk_mul_f32 v[58:59], v[58:59], v[246:247]
	v_pk_mul_f32 v[60:61], v[60:61], v[250:251]
	v_lshlrev_b32_e32 v246, 16, v86
	v_and_b32_e32 v247, 0xffff0000, v86
	v_lshlrev_b32_e32 v250, 16, v87
	v_and_b32_e32 v251, 0xffff0000, v87
	v_max_f32_e32 v246, 0x0da24260, v246
	v_max_f32_e32 v247, 0x0da24260, v247
	v_max_f32_e32 v250, 0x0da24260, v250
	v_max_f32_e32 v251, 0x0da24260, v251
	v_rcp_f32_e32 v246, v246
	v_rcp_f32_e32 v247, v247
	v_rcp_f32_e32 v250, v250
	v_rcp_f32_e32 v251, v251
	v_lshlrev_b32_e32 v244, 16, v82
	v_and_b32_e32 v245, 0xffff0000, v82
	v_lshlrev_b32_e32 v248, 16, v83
	v_and_b32_e32 v249, 0xffff0000, v83
	v_pk_mul_f32 v[54:55], v[54:55], v[244:245]
	v_pk_mul_f32 v[56:57], v[56:57], v[248:249]
	v_pk_mul_f32 v[54:55], v[54:55], v[246:247]
	v_pk_mul_f32 v[56:57], v[56:57], v[250:251]
	v_lshlrev_b32_e32 v246, 16, v88
	v_and_b32_e32 v247, 0xffff0000, v88
	v_lshlrev_b32_e32 v250, 16, v89
	v_and_b32_e32 v251, 0xffff0000, v89
	v_max_f32_e32 v246, 0x0da24260, v246
	v_max_f32_e32 v247, 0x0da24260, v247
	v_max_f32_e32 v250, 0x0da24260, v250
	v_max_f32_e32 v251, 0x0da24260, v251
	v_rcp_f32_e32 v246, v246
	v_rcp_f32_e32 v247, v247
	v_rcp_f32_e32 v250, v250
	v_rcp_f32_e32 v251, v251
	v_lshlrev_b32_e32 v244, 16, v84
	v_and_b32_e32 v245, 0xffff0000, v84
	v_lshlrev_b32_e32 v248, 16, v85
	v_and_b32_e32 v249, 0xffff0000, v85
	v_pk_mul_f32 v[50:51], v[50:51], v[244:245]
	v_pk_mul_f32 v[52:53], v[52:53], v[248:249]
	v_pk_mul_f32 v[50:51], v[50:51], v[246:247]
	v_pk_mul_f32 v[52:53], v[52:53], v[250:251]
	v_lshlrev_b32_e32 v246, 16, v94
	v_and_b32_e32 v247, 0xffff0000, v94
	v_lshlrev_b32_e32 v250, 16, v95
	v_and_b32_e32 v251, 0xffff0000, v95
	v_max_f32_e32 v246, 0x0da24260, v246
	v_max_f32_e32 v247, 0x0da24260, v247
	v_max_f32_e32 v250, 0x0da24260, v250
	v_max_f32_e32 v251, 0x0da24260, v251
	v_rcp_f32_e32 v246, v246
	v_rcp_f32_e32 v247, v247
	v_rcp_f32_e32 v250, v250
	v_rcp_f32_e32 v251, v251
	v_lshlrev_b32_e32 v244, 16, v90
	v_and_b32_e32 v245, 0xffff0000, v90
	v_lshlrev_b32_e32 v248, 16, v91
	v_and_b32_e32 v249, 0xffff0000, v91
	v_pk_mul_f32 v[46:47], v[46:47], v[244:245]
	v_pk_mul_f32 v[48:49], v[48:49], v[248:249]
	v_pk_mul_f32 v[46:47], v[46:47], v[246:247]
	v_pk_mul_f32 v[48:49], v[48:49], v[250:251]
	v_lshlrev_b32_e32 v246, 16, v96
	v_and_b32_e32 v247, 0xffff0000, v96
	v_lshlrev_b32_e32 v250, 16, v97
	v_and_b32_e32 v251, 0xffff0000, v97
	v_max_f32_e32 v246, 0x0da24260, v246
	v_max_f32_e32 v247, 0x0da24260, v247
	v_max_f32_e32 v250, 0x0da24260, v250
	v_max_f32_e32 v251, 0x0da24260, v251
	v_rcp_f32_e32 v246, v246
	v_rcp_f32_e32 v247, v247
	v_rcp_f32_e32 v250, v250
	v_rcp_f32_e32 v251, v251
	v_lshlrev_b32_e32 v244, 16, v92
	v_and_b32_e32 v245, 0xffff0000, v92
	v_lshlrev_b32_e32 v248, 16, v93
	v_and_b32_e32 v249, 0xffff0000, v93
	v_pk_mul_f32 v[42:43], v[42:43], v[244:245]
	v_pk_mul_f32 v[44:45], v[44:45], v[248:249]
	v_pk_mul_f32 v[42:43], v[42:43], v[246:247]
	v_pk_mul_f32 v[44:45], v[44:45], v[250:251]
	v_lshlrev_b32_e32 v246, 16, v110
	v_and_b32_e32 v247, 0xffff0000, v110
	v_lshlrev_b32_e32 v250, 16, v111
	v_and_b32_e32 v251, 0xffff0000, v111
	v_max_f32_e32 v246, 0x0da24260, v246
	v_max_f32_e32 v247, 0x0da24260, v247
	v_max_f32_e32 v250, 0x0da24260, v250
	v_max_f32_e32 v251, 0x0da24260, v251
	v_rcp_f32_e32 v246, v246
	v_rcp_f32_e32 v247, v247
	v_rcp_f32_e32 v250, v250
	v_rcp_f32_e32 v251, v251
	v_lshlrev_b32_e32 v244, 16, v106
	v_and_b32_e32 v245, 0xffff0000, v106
	v_lshlrev_b32_e32 v248, 16, v107
	v_and_b32_e32 v249, 0xffff0000, v107
	v_pk_mul_f32 v[38:39], v[38:39], v[244:245]
	v_pk_mul_f32 v[40:41], v[40:41], v[248:249]
	v_pk_mul_f32 v[38:39], v[38:39], v[246:247]
	v_pk_mul_f32 v[40:41], v[40:41], v[250:251]
	v_lshlrev_b32_e32 v246, 16, v112
	v_and_b32_e32 v247, 0xffff0000, v112
	v_lshlrev_b32_e32 v250, 16, v113
	v_and_b32_e32 v251, 0xffff0000, v113
	v_max_f32_e32 v246, 0x0da24260, v246
	v_max_f32_e32 v247, 0x0da24260, v247
	v_max_f32_e32 v250, 0x0da24260, v250
	v_max_f32_e32 v251, 0x0da24260, v251
	v_rcp_f32_e32 v246, v246
	v_rcp_f32_e32 v247, v247
	v_rcp_f32_e32 v250, v250
	v_rcp_f32_e32 v251, v251
	v_lshlrev_b32_e32 v244, 16, v108
	v_and_b32_e32 v245, 0xffff0000, v108
	v_lshlrev_b32_e32 v248, 16, v109
	v_and_b32_e32 v249, 0xffff0000, v109
	v_pk_mul_f32 v[34:35], v[34:35], v[244:245]
	v_pk_mul_f32 v[36:37], v[36:37], v[248:249]
	v_pk_mul_f32 v[34:35], v[34:35], v[246:247]
	v_pk_mul_f32 v[36:37], v[36:37], v[250:251]
	s_waitcnt vmcnt(0)
	v_lshlrev_b32_e32 v246, 16, v166
	v_and_b32_e32 v247, 0xffff0000, v166
	v_lshlrev_b32_e32 v250, 16, v167
	v_and_b32_e32 v251, 0xffff0000, v167
	v_max_f32_e32 v246, 0x0da24260, v246
	v_max_f32_e32 v247, 0x0da24260, v247
	v_max_f32_e32 v250, 0x0da24260, v250
	v_max_f32_e32 v251, 0x0da24260, v251
	v_rcp_f32_e32 v246, v246
	v_rcp_f32_e32 v247, v247
	v_rcp_f32_e32 v250, v250
	v_rcp_f32_e32 v251, v251
	v_lshlrev_b32_e32 v244, 16, v162
	v_and_b32_e32 v245, 0xffff0000, v162
	v_lshlrev_b32_e32 v248, 16, v163
	v_and_b32_e32 v249, 0xffff0000, v163
	v_pk_mul_f32 v[28:29], v[28:29], v[244:245]
	v_pk_mul_f32 v[30:31], v[30:31], v[248:249]
	v_pk_mul_f32 v[28:29], v[28:29], v[246:247]
	v_pk_mul_f32 v[30:31], v[30:31], v[250:251]
	v_lshlrev_b32_e32 v246, 16, v168
	v_and_b32_e32 v247, 0xffff0000, v168
	v_lshlrev_b32_e32 v250, 16, v169
	v_and_b32_e32 v251, 0xffff0000, v169
	v_max_f32_e32 v246, 0x0da24260, v246
	v_max_f32_e32 v247, 0x0da24260, v247
	v_max_f32_e32 v250, 0x0da24260, v250
	v_max_f32_e32 v251, 0x0da24260, v251
	v_rcp_f32_e32 v246, v246
	v_rcp_f32_e32 v247, v247
	v_rcp_f32_e32 v250, v250
	v_rcp_f32_e32 v251, v251
	v_lshlrev_b32_e32 v244, 16, v164
	v_and_b32_e32 v245, 0xffff0000, v164
	v_lshlrev_b32_e32 v248, 16, v165
	v_and_b32_e32 v249, 0xffff0000, v165
	v_pk_mul_f32 v[24:25], v[24:25], v[244:245]
	v_pk_mul_f32 v[26:27], v[26:27], v[248:249]
	v_pk_mul_f32 v[24:25], v[24:25], v[246:247]
	v_pk_mul_f32 v[26:27], v[26:27], v[250:251]
	v_lshlrev_b32_e32 v246, 16, v174
	v_and_b32_e32 v247, 0xffff0000, v174
	v_lshlrev_b32_e32 v250, 16, v175
	v_and_b32_e32 v251, 0xffff0000, v175
	v_max_f32_e32 v246, 0x0da24260, v246
	v_max_f32_e32 v247, 0x0da24260, v247
	v_max_f32_e32 v250, 0x0da24260, v250
	v_max_f32_e32 v251, 0x0da24260, v251
	v_rcp_f32_e32 v246, v246
	v_rcp_f32_e32 v247, v247
	v_rcp_f32_e32 v250, v250
	v_rcp_f32_e32 v251, v251
	v_lshlrev_b32_e32 v244, 16, v170
	v_and_b32_e32 v245, 0xffff0000, v170
	v_lshlrev_b32_e32 v248, 16, v171
	v_and_b32_e32 v249, 0xffff0000, v171
	v_pk_mul_f32 v[20:21], v[20:21], v[244:245]
	v_pk_mul_f32 v[22:23], v[22:23], v[248:249]
	v_pk_mul_f32 v[20:21], v[20:21], v[246:247]
	v_pk_mul_f32 v[22:23], v[22:23], v[250:251]
	v_lshlrev_b32_e32 v246, 16, v176
	v_and_b32_e32 v247, 0xffff0000, v176
	v_lshlrev_b32_e32 v250, 16, v177
	v_and_b32_e32 v251, 0xffff0000, v177
	v_max_f32_e32 v246, 0x0da24260, v246
	v_max_f32_e32 v247, 0x0da24260, v247
	v_max_f32_e32 v250, 0x0da24260, v250
	v_max_f32_e32 v251, 0x0da24260, v251
	v_rcp_f32_e32 v246, v246
	v_rcp_f32_e32 v247, v247
	v_rcp_f32_e32 v250, v250
	v_rcp_f32_e32 v251, v251
	v_lshlrev_b32_e32 v244, 16, v172
	v_and_b32_e32 v245, 0xffff0000, v172
	v_lshlrev_b32_e32 v248, 16, v173
	v_and_b32_e32 v249, 0xffff0000, v173
	v_pk_mul_f32 v[16:17], v[16:17], v[244:245]
	v_pk_mul_f32 v[18:19], v[18:19], v[248:249]
	v_pk_mul_f32 v[16:17], v[16:17], v[246:247]
	v_pk_mul_f32 v[18:19], v[18:19], v[250:251]
	v_lshlrev_b32_e32 v246, 16, v214
	v_and_b32_e32 v247, 0xffff0000, v214
	v_lshlrev_b32_e32 v250, 16, v215
	v_and_b32_e32 v251, 0xffff0000, v215
	v_max_f32_e32 v246, 0x0da24260, v246
	v_max_f32_e32 v247, 0x0da24260, v247
	v_max_f32_e32 v250, 0x0da24260, v250
	v_max_f32_e32 v251, 0x0da24260, v251
	v_rcp_f32_e32 v246, v246
	v_rcp_f32_e32 v247, v247
	v_rcp_f32_e32 v250, v250
	v_rcp_f32_e32 v251, v251
	v_lshlrev_b32_e32 v244, 16, v210
	v_and_b32_e32 v245, 0xffff0000, v210
	v_lshlrev_b32_e32 v248, 16, v211
	v_and_b32_e32 v249, 0xffff0000, v211
	v_pk_mul_f32 v[12:13], v[12:13], v[244:245]
	v_pk_mul_f32 v[14:15], v[14:15], v[248:249]
	v_pk_mul_f32 v[12:13], v[12:13], v[246:247]
	v_pk_mul_f32 v[14:15], v[14:15], v[250:251]
	v_lshlrev_b32_e32 v246, 16, v216
	v_and_b32_e32 v247, 0xffff0000, v216
	v_lshlrev_b32_e32 v250, 16, v217
	v_and_b32_e32 v251, 0xffff0000, v217
	v_max_f32_e32 v246, 0x0da24260, v246
	v_max_f32_e32 v247, 0x0da24260, v247
	v_max_f32_e32 v250, 0x0da24260, v250
	v_max_f32_e32 v251, 0x0da24260, v251
	v_rcp_f32_e32 v246, v246
	v_rcp_f32_e32 v247, v247
	v_rcp_f32_e32 v250, v250
	v_rcp_f32_e32 v251, v251
	v_lshlrev_b32_e32 v244, 16, v212
	v_and_b32_e32 v245, 0xffff0000, v212
	v_lshlrev_b32_e32 v248, 16, v213
	v_and_b32_e32 v249, 0xffff0000, v213
	v_pk_mul_f32 v[8:9], v[8:9], v[244:245]
	v_pk_mul_f32 v[10:11], v[10:11], v[248:249]
	v_pk_mul_f32 v[8:9], v[8:9], v[246:247]
	v_pk_mul_f32 v[10:11], v[10:11], v[250:251]
	v_lshlrev_b32_e32 v246, 16, v240
	v_and_b32_e32 v247, 0xffff0000, v240
	v_lshlrev_b32_e32 v250, 16, v241
	v_and_b32_e32 v251, 0xffff0000, v241
	v_max_f32_e32 v246, 0x0da24260, v246
	v_max_f32_e32 v247, 0x0da24260, v247
	v_max_f32_e32 v250, 0x0da24260, v250
	v_max_f32_e32 v251, 0x0da24260, v251
	v_rcp_f32_e32 v246, v246
	v_rcp_f32_e32 v247, v247
	v_rcp_f32_e32 v250, v250
	v_rcp_f32_e32 v251, v251
	v_lshlrev_b32_e32 v244, 16, v236
	v_and_b32_e32 v245, 0xffff0000, v236
	v_lshlrev_b32_e32 v248, 16, v237
	v_and_b32_e32 v249, 0xffff0000, v237
	v_pk_mul_f32 v[4:5], v[4:5], v[244:245]
	v_pk_mul_f32 v[6:7], v[6:7], v[248:249]
	v_pk_mul_f32 v[4:5], v[4:5], v[246:247]
	v_pk_mul_f32 v[6:7], v[6:7], v[250:251]
	v_lshlrev_b32_e32 v246, 16, v242
	v_and_b32_e32 v247, 0xffff0000, v242
	v_lshlrev_b32_e32 v250, 16, v243
	v_and_b32_e32 v251, 0xffff0000, v243
	v_max_f32_e32 v246, 0x0da24260, v246
	v_max_f32_e32 v247, 0x0da24260, v247
	v_max_f32_e32 v250, 0x0da24260, v250
	v_max_f32_e32 v251, 0x0da24260, v251
	v_rcp_f32_e32 v246, v246
	v_rcp_f32_e32 v247, v247
	v_rcp_f32_e32 v250, v250
	v_rcp_f32_e32 v251, v251
	v_lshlrev_b32_e32 v244, 16, v238
	v_and_b32_e32 v245, 0xffff0000, v238
	v_lshlrev_b32_e32 v248, 16, v239
	v_and_b32_e32 v249, 0xffff0000, v239
	v_pk_mul_f32 v[0:1], v[0:1], v[244:245]
	v_pk_mul_f32 v[2:3], v[2:3], v[248:249]
	v_pk_mul_f32 v[0:1], v[0:1], v[246:247]
	v_pk_mul_f32 v[2:3], v[2:3], v[250:251]
	s_branch .LBB0_1183
